# v48 plus P1 epilogue plain f32 VALU pairs merged into v_pk_mul/add/fma_f32 (same f32 math, half the issue slots)
# baseline (speedup 1.0000x reference)
; __device__ __forceinline__ unsigned cvt_pk_bf16(float lo, float hi) { unsigned r; asm volatile("v_cvt_pk_bf16_f32 %0, %1, %2" : "=v"(r) : "v"(lo), "v"(hi)); return r; }
; __device__ __forceinline__ float sigmoid_f(float x) { return __builtin_amdgcn_rcpf(1.0f + __builtin_amdgcn_exp2f(-1.4426950409f * x)); }
;     __device__ __forceinline__ void operator()(f32x4 (&acc)[2][2][4][2], const Unit& u, int wr, int wc, int fr, int fq) const {
;     ...
;         const int row0 = u.pm * BM + wr * 64 + fr; const size_t col0 = ocol + wc * 32 + 8 * fq;
;         if (mode >= 4) {
; #pragma unroll
;             for (int ai = 0; ai < 2; ++ai)
; #pragma unroll
;                 for (int m = 0; m < 4; ++m) { bf16_t* rowp = O + (size_t)(row0 + ai * HALF + m * 16) * LDP + col0;
;                     float v[8];
; #pragma unroll
;                     for (int j = 0; j < 8; ++j) {
;                         const float x0 = acc[ai][0][m][j >> 2][j & 3], x1 = acc[ai][1][m][j >> 2][j & 3];
;                         const float f0 = (mode == 4) ? x0 * sigmoid_f(1.5957691216f * (x0 + 0.044715f * x0 * x0 * x0)) : x0;
;                         const float f1 = (mode == 5) ? x1 : x1 * sigmoid_f(x1);
;                         v[j] = f0 * f1;
;                     }
;                     u32x4 w; w.x = cvt_pk_bf16(v[0], v[1]); w.y = cvt_pk_bf16(v[2], v[3]); w.z = cvt_pk_bf16(v[4], v[5]); w.w = cvt_pk_bf16(v[6], v[7]);
;                     *(u32x4*)rowp = w; }
.LBB0_283:
	s_mov_b32 s62, 0xbfb8aa3b
	s_mov_b32 s63, 0xbfb8aa3b
	s_mov_b32 s64, 1.0
	s_mov_b32 s65, 1.0
	v_lshl_add_u32 v148, s60, 8, v164
	v_ashrrev_i32_e32 v149, 31, v148
	s_cmp_gt_u32 s59, 31
	s_cbranch_scc1 .LBB0_424
	v_lshlrev_b32_e32 v150, 11, v164
	v_lshl_add_u32 v150, v136, 1, v150
	s_lshl_b32 s14, s60, 19
	s_add_u32 s24, s70, s14
	s_addc_u32 s25, s71, 0
	s_cmp_lt_u32 s59, 8
	s_cbranch_scc1 .Lp1_epi_m4
	s_cmp_lt_u32 s59, 12
	s_cbranch_scc1 .Lp1_epi_m1
	s_cmp_lt_u32 s59, 16
	s_cbranch_scc1 .Lp1_epi_m0
	s_cmp_lt_u32 s59, 24
	s_cbranch_scc1 .Lp1_epi_m5
.Lp1_epi_m6:
	s_lshl_b32 s14, s59, 8
	s_add_u32 s14, s14, 0x17ffe800
	s_add_u32 s24, s24, s14
	s_addc_u32 s25, s25, 0
	v_pk_mul_f32 v[168:169], v[116:117], s[62:63]
	v_pk_mul_f32 v[170:171], v[118:119], s[62:63]
	v_pk_mul_f32 v[172:173], v[112:113], s[62:63]
	v_pk_mul_f32 v[174:175], v[114:115], s[62:63]
	v_exp_f32_e32 v168, v168
	v_exp_f32_e32 v169, v169
	v_exp_f32_e32 v170, v170
	v_exp_f32_e32 v171, v171
	v_exp_f32_e32 v172, v172
	v_exp_f32_e32 v173, v173
	v_exp_f32_e32 v174, v174
	v_exp_f32_e32 v175, v175
	v_pk_mul_f32 v[152:153], v[124:125], v[116:117]
	v_pk_mul_f32 v[154:155], v[126:127], v[118:119]
	v_pk_mul_f32 v[156:157], v[120:121], v[112:113]
	v_pk_mul_f32 v[158:159], v[122:123], v[114:115]
	v_pk_add_f32 v[168:169], v[168:169], s[64:65]
	v_pk_add_f32 v[170:171], v[170:171], s[64:65]
	v_pk_add_f32 v[172:173], v[172:173], s[64:65]
	v_pk_add_f32 v[174:175], v[174:175], s[64:65]
	v_rcp_f32_e32 v168, v168
	v_rcp_f32_e32 v169, v169
	v_rcp_f32_e32 v170, v170
	v_rcp_f32_e32 v171, v171
	v_rcp_f32_e32 v172, v172
	v_rcp_f32_e32 v173, v173
	v_rcp_f32_e32 v174, v174
	v_rcp_f32_e32 v175, v175
	s_nop 0
	v_pk_mul_f32 v[152:153], v[152:153], v[168:169]
	v_pk_mul_f32 v[154:155], v[154:155], v[170:171]
	v_pk_mul_f32 v[156:157], v[156:157], v[172:173]
	v_pk_mul_f32 v[158:159], v[158:159], v[174:175]
	v_cvt_pk_bf16_f32 v176, v152, v153
	v_cvt_pk_bf16_f32 v177, v154, v155
	v_cvt_pk_bf16_f32 v178, v156, v157
	v_cvt_pk_bf16_f32 v179, v158, v159
	global_store_dwordx4 v150, v[176:179], s[24:25]
	s_add_u32 s24, s24, 0x8000
	s_addc_u32 s25, s25, 0
	v_pk_mul_f32 v[168:169], v[100:101], s[62:63]
	v_pk_mul_f32 v[170:171], v[102:103], s[62:63]
	v_pk_mul_f32 v[172:173], v[96:97], s[62:63]
	v_pk_mul_f32 v[174:175], v[98:99], s[62:63]
	v_exp_f32_e32 v168, v168
	v_exp_f32_e32 v169, v169
	v_exp_f32_e32 v170, v170
	v_exp_f32_e32 v171, v171
	v_exp_f32_e32 v172, v172
	v_exp_f32_e32 v173, v173
	v_exp_f32_e32 v174, v174
	v_exp_f32_e32 v175, v175
	v_pk_mul_f32 v[152:153], v[108:109], v[100:101]
	v_pk_mul_f32 v[154:155], v[110:111], v[102:103]
	v_pk_mul_f32 v[156:157], v[104:105], v[96:97]
	v_pk_mul_f32 v[158:159], v[106:107], v[98:99]
	v_pk_add_f32 v[168:169], v[168:169], s[64:65]
	v_pk_add_f32 v[170:171], v[170:171], s[64:65]
	v_pk_add_f32 v[172:173], v[172:173], s[64:65]
	v_pk_add_f32 v[174:175], v[174:175], s[64:65]
	v_rcp_f32_e32 v168, v168
	v_rcp_f32_e32 v169, v169
	v_rcp_f32_e32 v170, v170
	v_rcp_f32_e32 v171, v171
	v_rcp_f32_e32 v172, v172
	v_rcp_f32_e32 v173, v173
	v_rcp_f32_e32 v174, v174
	v_rcp_f32_e32 v175, v175
	s_nop 0
	v_pk_mul_f32 v[152:153], v[152:153], v[168:169]
	v_pk_mul_f32 v[154:155], v[154:155], v[170:171]
	v_pk_mul_f32 v[156:157], v[156:157], v[172:173]
	v_pk_mul_f32 v[158:159], v[158:159], v[174:175]
	v_cvt_pk_bf16_f32 v180, v152, v153
	v_cvt_pk_bf16_f32 v181, v154, v155
	v_cvt_pk_bf16_f32 v182, v156, v157
	v_cvt_pk_bf16_f32 v183, v158, v159
	global_store_dwordx4 v150, v[180:183], s[24:25]
	s_add_u32 s24, s24, 0x8000
	s_addc_u32 s25, s25, 0
	v_pk_mul_f32 v[168:169], v[84:85], s[62:63]
	v_pk_mul_f32 v[170:171], v[86:87], s[62:63]
	v_pk_mul_f32 v[172:173], v[80:81], s[62:63]
	v_pk_mul_f32 v[174:175], v[82:83], s[62:63]
	v_exp_f32_e32 v168, v168
	v_exp_f32_e32 v169, v169
	v_exp_f32_e32 v170, v170
	v_exp_f32_e32 v171, v171
	v_exp_f32_e32 v172, v172
	v_exp_f32_e32 v173, v173
	v_exp_f32_e32 v174, v174
	v_exp_f32_e32 v175, v175
	v_pk_mul_f32 v[152:153], v[92:93], v[84:85]
	v_pk_mul_f32 v[154:155], v[94:95], v[86:87]
	v_pk_mul_f32 v[156:157], v[88:89], v[80:81]
	v_pk_mul_f32 v[158:159], v[90:91], v[82:83]
	v_pk_add_f32 v[168:169], v[168:169], s[64:65]
	v_pk_add_f32 v[170:171], v[170:171], s[64:65]
	v_pk_add_f32 v[172:173], v[172:173], s[64:65]
	v_pk_add_f32 v[174:175], v[174:175], s[64:65]
	v_rcp_f32_e32 v168, v168
	v_rcp_f32_e32 v169, v169
	v_rcp_f32_e32 v170, v170
	v_rcp_f32_e32 v171, v171
	v_rcp_f32_e32 v172, v172
	v_rcp_f32_e32 v173, v173
	v_rcp_f32_e32 v174, v174
	v_rcp_f32_e32 v175, v175
	s_nop 0
	v_pk_mul_f32 v[152:153], v[152:153], v[168:169]
	v_pk_mul_f32 v[154:155], v[154:155], v[170:171]
	v_pk_mul_f32 v[156:157], v[156:157], v[172:173]
	v_pk_mul_f32 v[158:159], v[158:159], v[174:175]
	v_cvt_pk_bf16_f32 v176, v152, v153
	v_cvt_pk_bf16_f32 v177, v154, v155
	v_cvt_pk_bf16_f32 v178, v156, v157
	v_cvt_pk_bf16_f32 v179, v158, v159
	global_store_dwordx4 v150, v[176:179], s[24:25]
	s_add_u32 s24, s24, 0x8000
	s_addc_u32 s25, s25, 0
	v_pk_mul_f32 v[168:169], v[68:69], s[62:63]
	v_pk_mul_f32 v[170:171], v[70:71], s[62:63]
	v_pk_mul_f32 v[172:173], v[64:65], s[62:63]
	v_pk_mul_f32 v[174:175], v[66:67], s[62:63]
	v_exp_f32_e32 v168, v168
	v_exp_f32_e32 v169, v169
	v_exp_f32_e32 v170, v170
	v_exp_f32_e32 v171, v171
	v_exp_f32_e32 v172, v172
	v_exp_f32_e32 v173, v173
	v_exp_f32_e32 v174, v174
	v_exp_f32_e32 v175, v175
	v_pk_mul_f32 v[152:153], v[76:77], v[68:69]
	v_pk_mul_f32 v[154:155], v[78:79], v[70:71]
	v_pk_mul_f32 v[156:157], v[72:73], v[64:65]
	v_pk_mul_f32 v[158:159], v[74:75], v[66:67]
	v_pk_add_f32 v[168:169], v[168:169], s[64:65]
	v_pk_add_f32 v[170:171], v[170:171], s[64:65]
; __device__ __forceinline__ unsigned cvt_pk_bf16(float lo, float hi) { unsigned r; asm volatile("v_cvt_pk_bf16_f32 %0, %1, %2" : "=v"(r) : "v"(lo), "v"(hi)); return r; }
; __device__ __forceinline__ float sigmoid_f(float x) { return __builtin_amdgcn_rcpf(1.0f + __builtin_amdgcn_exp2f(-1.4426950409f * x)); }
;     __device__ __forceinline__ void operator()(f32x4 (&acc)[2][2][4][2], const Unit& u, int wr, int wc, int fr, int fq) const {
;     ...
;         const int row0 = u.pm * BM + wr * 64 + fr; const size_t col0 = ocol + wc * 32 + 8 * fq;
;         if (mode >= 4) {
; #pragma unroll
;             for (int ai = 0; ai < 2; ++ai)
; #pragma unroll
;                 for (int m = 0; m < 4; ++m) { bf16_t* rowp = O + (size_t)(row0 + ai * HALF + m * 16) * LDP + col0;
;                     float v[8];
; #pragma unroll
;                     for (int j = 0; j < 8; ++j) {
;                         const float x0 = acc[ai][0][m][j >> 2][j & 3], x1 = acc[ai][1][m][j >> 2][j & 3];
;                         const float f0 = (mode == 4) ? x0 * sigmoid_f(1.5957691216f * (x0 + 0.044715f * x0 * x0 * x0)) : x0;
;                         const float f1 = (mode == 5) ? x1 : x1 * sigmoid_f(x1);
;                         v[j] = f0 * f1;
;                     }
;                     u32x4 w; w.x = cvt_pk_bf16(v[0], v[1]); w.y = cvt_pk_bf16(v[2], v[3]); w.z = cvt_pk_bf16(v[4], v[5]); w.w = cvt_pk_bf16(v[6], v[7]);
;                     *(u32x4*)rowp = w; }
	v_pk_add_f32 v[172:173], v[172:173], s[64:65]
	v_pk_add_f32 v[174:175], v[174:175], s[64:65]
	v_rcp_f32_e32 v168, v168
	v_rcp_f32_e32 v169, v169
	v_rcp_f32_e32 v170, v170
	v_rcp_f32_e32 v171, v171
	v_rcp_f32_e32 v172, v172
	v_rcp_f32_e32 v173, v173
	v_rcp_f32_e32 v174, v174
	v_rcp_f32_e32 v175, v175
	s_nop 0
	v_pk_mul_f32 v[152:153], v[152:153], v[168:169]
	v_pk_mul_f32 v[154:155], v[154:155], v[170:171]
	v_pk_mul_f32 v[156:157], v[156:157], v[172:173]
	v_pk_mul_f32 v[158:159], v[158:159], v[174:175]
	v_cvt_pk_bf16_f32 v180, v152, v153
	v_cvt_pk_bf16_f32 v181, v154, v155
	v_cvt_pk_bf16_f32 v182, v156, v157
	v_cvt_pk_bf16_f32 v183, v158, v159
	global_store_dwordx4 v150, v[180:183], s[24:25]
	s_add_u32 s24, s24, 0x28000
	s_addc_u32 s25, s25, 0
	v_pk_mul_f32 v[168:169], v[52:53], s[62:63]
	v_pk_mul_f32 v[170:171], v[54:55], s[62:63]
	v_pk_mul_f32 v[172:173], v[48:49], s[62:63]
	v_pk_mul_f32 v[174:175], v[50:51], s[62:63]
	v_exp_f32_e32 v168, v168
	v_exp_f32_e32 v169, v169
	v_exp_f32_e32 v170, v170
	v_exp_f32_e32 v171, v171
	v_exp_f32_e32 v172, v172
	v_exp_f32_e32 v173, v173
	v_exp_f32_e32 v174, v174
	v_exp_f32_e32 v175, v175
	v_pk_mul_f32 v[152:153], v[60:61], v[52:53]
	v_pk_mul_f32 v[154:155], v[62:63], v[54:55]
	v_pk_mul_f32 v[156:157], v[56:57], v[48:49]
	v_pk_mul_f32 v[158:159], v[58:59], v[50:51]
	v_pk_add_f32 v[168:169], v[168:169], s[64:65]
	v_pk_add_f32 v[170:171], v[170:171], s[64:65]
	v_pk_add_f32 v[172:173], v[172:173], s[64:65]
	v_pk_add_f32 v[174:175], v[174:175], s[64:65]
	v_rcp_f32_e32 v168, v168
	v_rcp_f32_e32 v169, v169
	v_rcp_f32_e32 v170, v170
	v_rcp_f32_e32 v171, v171
	v_rcp_f32_e32 v172, v172
	v_rcp_f32_e32 v173, v173
	v_rcp_f32_e32 v174, v174
	v_rcp_f32_e32 v175, v175
	s_nop 0
	v_pk_mul_f32 v[152:153], v[152:153], v[168:169]
	v_pk_mul_f32 v[154:155], v[154:155], v[170:171]
	v_pk_mul_f32 v[156:157], v[156:157], v[172:173]
	v_pk_mul_f32 v[158:159], v[158:159], v[174:175]
	v_cvt_pk_bf16_f32 v176, v152, v153
	v_cvt_pk_bf16_f32 v177, v154, v155
	v_cvt_pk_bf16_f32 v178, v156, v157
	v_cvt_pk_bf16_f32 v179, v158, v159
	global_store_dwordx4 v150, v[176:179], s[24:25]
	s_add_u32 s24, s24, 0x8000
	s_addc_u32 s25, s25, 0
	v_pk_mul_f32 v[168:169], v[36:37], s[62:63]
	v_pk_mul_f32 v[170:171], v[38:39], s[62:63]
	v_pk_mul_f32 v[172:173], v[32:33], s[62:63]
	v_pk_mul_f32 v[174:175], v[34:35], s[62:63]
	v_exp_f32_e32 v168, v168
	v_exp_f32_e32 v169, v169
	v_exp_f32_e32 v170, v170
	v_exp_f32_e32 v171, v171
	v_exp_f32_e32 v172, v172
	v_exp_f32_e32 v173, v173
	v_exp_f32_e32 v174, v174
	v_exp_f32_e32 v175, v175
	v_pk_mul_f32 v[152:153], v[44:45], v[36:37]
	v_pk_mul_f32 v[154:155], v[46:47], v[38:39]
	v_pk_mul_f32 v[156:157], v[40:41], v[32:33]
	v_pk_mul_f32 v[158:159], v[42:43], v[34:35]
	v_pk_add_f32 v[168:169], v[168:169], s[64:65]
	v_pk_add_f32 v[170:171], v[170:171], s[64:65]
	v_pk_add_f32 v[172:173], v[172:173], s[64:65]
	v_pk_add_f32 v[174:175], v[174:175], s[64:65]
	v_rcp_f32_e32 v168, v168
	v_rcp_f32_e32 v169, v169
	v_rcp_f32_e32 v170, v170
	v_rcp_f32_e32 v171, v171
	v_rcp_f32_e32 v172, v172
	v_rcp_f32_e32 v173, v173
	v_rcp_f32_e32 v174, v174
	v_rcp_f32_e32 v175, v175
	s_nop 0
	v_pk_mul_f32 v[152:153], v[152:153], v[168:169]
	v_pk_mul_f32 v[154:155], v[154:155], v[170:171]
	v_pk_mul_f32 v[156:157], v[156:157], v[172:173]
	v_pk_mul_f32 v[158:159], v[158:159], v[174:175]
	v_cvt_pk_bf16_f32 v180, v152, v153
	v_cvt_pk_bf16_f32 v181, v154, v155
	v_cvt_pk_bf16_f32 v182, v156, v157
	v_cvt_pk_bf16_f32 v183, v158, v159
	global_store_dwordx4 v150, v[180:183], s[24:25]
	s_add_u32 s24, s24, 0x8000
	s_addc_u32 s25, s25, 0
	v_pk_mul_f32 v[168:169], v[20:21], s[62:63]
	v_pk_mul_f32 v[170:171], v[22:23], s[62:63]
	v_pk_mul_f32 v[172:173], v[16:17], s[62:63]
	v_pk_mul_f32 v[174:175], v[18:19], s[62:63]
	v_exp_f32_e32 v168, v168
	v_exp_f32_e32 v169, v169
	v_exp_f32_e32 v170, v170
	v_exp_f32_e32 v171, v171
	v_exp_f32_e32 v172, v172
	v_exp_f32_e32 v173, v173
	v_exp_f32_e32 v174, v174
	v_exp_f32_e32 v175, v175
	v_pk_mul_f32 v[152:153], v[28:29], v[20:21]
	v_pk_mul_f32 v[154:155], v[30:31], v[22:23]
	v_pk_mul_f32 v[156:157], v[24:25], v[16:17]
	v_pk_mul_f32 v[158:159], v[26:27], v[18:19]
	v_pk_add_f32 v[168:169], v[168:169], s[64:65]
	v_pk_add_f32 v[170:171], v[170:171], s[64:65]
	v_pk_add_f32 v[172:173], v[172:173], s[64:65]
	v_pk_add_f32 v[174:175], v[174:175], s[64:65]
	v_rcp_f32_e32 v168, v168
	v_rcp_f32_e32 v169, v169
	v_rcp_f32_e32 v170, v170
	v_rcp_f32_e32 v171, v171
	v_rcp_f32_e32 v172, v172
	v_rcp_f32_e32 v173, v173
	v_rcp_f32_e32 v174, v174
	v_rcp_f32_e32 v175, v175
	s_nop 0
	v_pk_mul_f32 v[152:153], v[152:153], v[168:169]
	v_pk_mul_f32 v[154:155], v[154:155], v[170:171]
	v_pk_mul_f32 v[156:157], v[156:157], v[172:173]
	v_pk_mul_f32 v[158:159], v[158:159], v[174:175]
	v_cvt_pk_bf16_f32 v176, v152, v153
	v_cvt_pk_bf16_f32 v177, v154, v155
	v_cvt_pk_bf16_f32 v178, v156, v157
	v_cvt_pk_bf16_f32 v179, v158, v159
	global_store_dwordx4 v150, v[176:179], s[24:25]
	s_add_u32 s24, s24, 0x8000
	s_addc_u32 s25, s25, 0
	v_pk_mul_f32 v[168:169], v[4:5], s[62:63]
	v_pk_mul_f32 v[170:171], v[6:7], s[62:63]
	v_pk_mul_f32 v[172:173], v[0:1], s[62:63]
	v_pk_mul_f32 v[174:175], v[2:3], s[62:63]
	v_exp_f32_e32 v168, v168
	v_exp_f32_e32 v169, v169
	v_exp_f32_e32 v170, v170
	v_exp_f32_e32 v171, v171
	v_exp_f32_e32 v172, v172
	v_exp_f32_e32 v173, v173
	v_exp_f32_e32 v174, v174
	v_exp_f32_e32 v175, v175
	v_pk_mul_f32 v[152:153], v[12:13], v[4:5]
	v_pk_mul_f32 v[154:155], v[14:15], v[6:7]
	v_pk_mul_f32 v[156:157], v[8:9], v[0:1]
	v_pk_mul_f32 v[158:159], v[10:11], v[2:3]
	v_pk_add_f32 v[168:169], v[168:169], s[64:65]
	v_pk_add_f32 v[170:171], v[170:171], s[64:65]
	v_pk_add_f32 v[172:173], v[172:173], s[64:65]
	v_pk_add_f32 v[174:175], v[174:175], s[64:65]
	v_rcp_f32_e32 v168, v168
	v_rcp_f32_e32 v169, v169
	v_rcp_f32_e32 v170, v170
	v_rcp_f32_e32 v171, v171
	v_rcp_f32_e32 v172, v172
	v_rcp_f32_e32 v173, v173
	v_rcp_f32_e32 v174, v174
	v_rcp_f32_e32 v175, v175
	s_nop 0
	v_pk_mul_f32 v[152:153], v[152:153], v[168:169]
	v_pk_mul_f32 v[154:155], v[154:155], v[170:171]
	v_pk_mul_f32 v[156:157], v[156:157], v[172:173]
	v_pk_mul_f32 v[158:159], v[158:159], v[174:175]
	v_cvt_pk_bf16_f32 v180, v152, v153
	v_cvt_pk_bf16_f32 v181, v154, v155
	v_cvt_pk_bf16_f32 v182, v156, v157
	v_cvt_pk_bf16_f32 v183, v158, v159
	global_store_dwordx4 v150, v[180:183], s[24:25]
	s_branch .LBB0_298
; __device__ __forceinline__ unsigned cvt_pk_bf16(float lo, float hi) { unsigned r; asm volatile("v_cvt_pk_bf16_f32 %0, %1, %2" : "=v"(r) : "v"(lo), "v"(hi)); return r; }
; __device__ __forceinline__ float sigmoid_f(float x) { return __builtin_amdgcn_rcpf(1.0f + __builtin_amdgcn_exp2f(-1.4426950409f * x)); }
;     __device__ __forceinline__ void operator()(f32x4 (&acc)[2][2][4][2], const Unit& u, int wr, int wc, int fr, int fq) const {
;     ...
;         const int row0 = u.pm * BM + wr * 64 + fr; const size_t col0 = ocol + wc * 32 + 8 * fq;
;         if (mode >= 4) {
; #pragma unroll
;             for (int ai = 0; ai < 2; ++ai)
; #pragma unroll
;                 for (int m = 0; m < 4; ++m) { bf16_t* rowp = O + (size_t)(row0 + ai * HALF + m * 16) * LDP + col0;
;                     float v[8];
; #pragma unroll
;                     for (int j = 0; j < 8; ++j) {
;                         const float x0 = acc[ai][0][m][j >> 2][j & 3], x1 = acc[ai][1][m][j >> 2][j & 3];
;                         const float f0 = (mode == 4) ? x0 * sigmoid_f(1.5957691216f * (x0 + 0.044715f * x0 * x0 * x0)) : x0;
;                         const float f1 = (mode == 5) ? x1 : x1 * sigmoid_f(x1);
;                         v[j] = f0 * f1;
;                     }
;                     u32x4 w; w.x = cvt_pk_bf16(v[0], v[1]); w.y = cvt_pk_bf16(v[2], v[3]); w.z = cvt_pk_bf16(v[4], v[5]); w.w = cvt_pk_bf16(v[6], v[7]);
;                     *(u32x4*)rowp = w; }
.Lp1_epi_m5:
	s_lshl_b32 s14, s59, 8
	s_add_u32 s14, s14, 0xffff000
	s_add_u32 s24, s24, s14
	s_addc_u32 s25, s25, 0
	v_pk_mul_f32 v[152:153], v[124:125], v[116:117]
	v_pk_mul_f32 v[154:155], v[126:127], v[118:119]
	v_pk_mul_f32 v[156:157], v[120:121], v[112:113]
	v_pk_mul_f32 v[158:159], v[122:123], v[114:115]
	v_cvt_pk_bf16_f32 v176, v152, v153
	v_cvt_pk_bf16_f32 v177, v154, v155
	v_cvt_pk_bf16_f32 v178, v156, v157
	v_cvt_pk_bf16_f32 v179, v158, v159
	global_store_dwordx4 v150, v[176:179], s[24:25]
	s_add_u32 s24, s24, 0x8000
	s_addc_u32 s25, s25, 0
	v_pk_mul_f32 v[152:153], v[108:109], v[100:101]
	v_pk_mul_f32 v[154:155], v[110:111], v[102:103]
	v_pk_mul_f32 v[156:157], v[104:105], v[96:97]
	v_pk_mul_f32 v[158:159], v[106:107], v[98:99]
	v_cvt_pk_bf16_f32 v180, v152, v153
	v_cvt_pk_bf16_f32 v181, v154, v155
	v_cvt_pk_bf16_f32 v182, v156, v157
	v_cvt_pk_bf16_f32 v183, v158, v159
	global_store_dwordx4 v150, v[180:183], s[24:25]
	s_add_u32 s24, s24, 0x8000
	s_addc_u32 s25, s25, 0
	v_pk_mul_f32 v[152:153], v[92:93], v[84:85]
	v_pk_mul_f32 v[154:155], v[94:95], v[86:87]
	v_pk_mul_f32 v[156:157], v[88:89], v[80:81]
	v_pk_mul_f32 v[158:159], v[90:91], v[82:83]
	v_cvt_pk_bf16_f32 v176, v152, v153
	v_cvt_pk_bf16_f32 v177, v154, v155
	v_cvt_pk_bf16_f32 v178, v156, v157
	v_cvt_pk_bf16_f32 v179, v158, v159
	global_store_dwordx4 v150, v[176:179], s[24:25]
	s_add_u32 s24, s24, 0x8000
	s_addc_u32 s25, s25, 0
	v_pk_mul_f32 v[152:153], v[76:77], v[68:69]
	v_pk_mul_f32 v[154:155], v[78:79], v[70:71]
	v_pk_mul_f32 v[156:157], v[72:73], v[64:65]
	v_pk_mul_f32 v[158:159], v[74:75], v[66:67]
	v_cvt_pk_bf16_f32 v180, v152, v153
	v_cvt_pk_bf16_f32 v181, v154, v155
	v_cvt_pk_bf16_f32 v182, v156, v157
	v_cvt_pk_bf16_f32 v183, v158, v159
	global_store_dwordx4 v150, v[180:183], s[24:25]
	s_add_u32 s24, s24, 0x28000
	s_addc_u32 s25, s25, 0
	v_pk_mul_f32 v[152:153], v[60:61], v[52:53]
	v_pk_mul_f32 v[154:155], v[62:63], v[54:55]
	v_pk_mul_f32 v[156:157], v[56:57], v[48:49]
	v_pk_mul_f32 v[158:159], v[58:59], v[50:51]
	v_cvt_pk_bf16_f32 v176, v152, v153
	v_cvt_pk_bf16_f32 v177, v154, v155
	v_cvt_pk_bf16_f32 v178, v156, v157
	v_cvt_pk_bf16_f32 v179, v158, v159
	global_store_dwordx4 v150, v[176:179], s[24:25]
	s_add_u32 s24, s24, 0x8000
	s_addc_u32 s25, s25, 0
	v_pk_mul_f32 v[152:153], v[44:45], v[36:37]
	v_pk_mul_f32 v[154:155], v[46:47], v[38:39]
	v_pk_mul_f32 v[156:157], v[40:41], v[32:33]
	v_pk_mul_f32 v[158:159], v[42:43], v[34:35]
	v_cvt_pk_bf16_f32 v180, v152, v153
	v_cvt_pk_bf16_f32 v181, v154, v155
	v_cvt_pk_bf16_f32 v182, v156, v157
	v_cvt_pk_bf16_f32 v183, v158, v159
	global_store_dwordx4 v150, v[180:183], s[24:25]
	s_add_u32 s24, s24, 0x8000
	s_addc_u32 s25, s25, 0
	v_pk_mul_f32 v[152:153], v[28:29], v[20:21]
	v_pk_mul_f32 v[154:155], v[30:31], v[22:23]
	v_pk_mul_f32 v[156:157], v[24:25], v[16:17]
	v_pk_mul_f32 v[158:159], v[26:27], v[18:19]
	v_cvt_pk_bf16_f32 v176, v152, v153
	v_cvt_pk_bf16_f32 v177, v154, v155
	v_cvt_pk_bf16_f32 v178, v156, v157
	v_cvt_pk_bf16_f32 v179, v158, v159
	global_store_dwordx4 v150, v[176:179], s[24:25]
	s_add_u32 s24, s24, 0x8000
	s_addc_u32 s25, s25, 0
	v_pk_mul_f32 v[152:153], v[12:13], v[4:5]
	v_pk_mul_f32 v[154:155], v[14:15], v[6:7]
	v_pk_mul_f32 v[156:157], v[8:9], v[0:1]
	v_pk_mul_f32 v[158:159], v[10:11], v[2:3]
	v_cvt_pk_bf16_f32 v180, v152, v153
	v_cvt_pk_bf16_f32 v181, v154, v155
	v_cvt_pk_bf16_f32 v182, v156, v157
	v_cvt_pk_bf16_f32 v183, v158, v159
	global_store_dwordx4 v150, v[180:183], s[24:25]
	s_branch .LBB0_298
.Lp1_epi_m4:
	s_lshl_b32 s14, s59, 8
	s_add_u32 s24, s24, s14
	s_addc_u32 s25, s25, 0
	v_mov_b32_e32 v151, 0xbdd2d3e8
	v_pk_mul_f32 v[152:153], v[124:125], v[124:125]
	v_pk_mul_f32 v[154:155], v[126:127], v[126:127]
	v_pk_mul_f32 v[156:157], v[120:121], v[120:121]
	v_pk_mul_f32 v[158:159], v[122:123], v[122:123]
	v_pk_mul_f32 v[168:169], v[116:117], s[62:63]
	v_pk_mul_f32 v[170:171], v[118:119], s[62:63]
	v_pk_mul_f32 v[172:173], v[112:113], s[62:63]
	v_pk_mul_f32 v[174:175], v[114:115], s[62:63]
	v_fmaak_f32 v152, v151, v152, 0xc0135761
	v_fmaak_f32 v153, v151, v153, 0xc0135761
	v_fmaak_f32 v154, v151, v154, 0xc0135761
	v_fmaak_f32 v155, v151, v155, 0xc0135761
	v_fmaak_f32 v156, v151, v156, 0xc0135761
	v_fmaak_f32 v157, v151, v157, 0xc0135761
	v_fmaak_f32 v158, v151, v158, 0xc0135761
	v_fmaak_f32 v159, v151, v159, 0xc0135761
	v_exp_f32_e32 v168, v168
	v_exp_f32_e32 v169, v169
	v_exp_f32_e32 v170, v170
	v_exp_f32_e32 v171, v171
	v_exp_f32_e32 v172, v172
	v_exp_f32_e32 v173, v173
	v_exp_f32_e32 v174, v174
	v_exp_f32_e32 v175, v175
	v_pk_mul_f32 v[152:153], v[124:125], v[152:153]
	v_pk_mul_f32 v[154:155], v[126:127], v[154:155]
	v_pk_mul_f32 v[156:157], v[120:121], v[156:157]
	v_pk_mul_f32 v[158:159], v[122:123], v[158:159]
	v_exp_f32_e32 v152, v152
	v_exp_f32_e32 v153, v153
	v_exp_f32_e32 v154, v154
	v_exp_f32_e32 v155, v155
	v_exp_f32_e32 v156, v156
	v_exp_f32_e32 v157, v157
	v_exp_f32_e32 v158, v158
	v_exp_f32_e32 v159, v159
	v_pk_add_f32 v[168:169], v[168:169], s[64:65]
	v_pk_add_f32 v[170:171], v[170:171], s[64:65]
	v_pk_add_f32 v[172:173], v[172:173], s[64:65]
	v_pk_add_f32 v[174:175], v[174:175], s[64:65]
	v_pk_fma_f32 v[152:153], v[152:153], v[168:169], v[168:169]
	v_pk_fma_f32 v[154:155], v[154:155], v[170:171], v[170:171]
	v_pk_fma_f32 v[156:157], v[156:157], v[172:173], v[172:173]
	v_pk_fma_f32 v[158:159], v[158:159], v[174:175], v[174:175]
	v_pk_mul_f32 v[168:169], v[124:125], v[116:117]
	v_pk_mul_f32 v[170:171], v[126:127], v[118:119]
	v_pk_mul_f32 v[172:173], v[120:121], v[112:113]
	v_pk_mul_f32 v[174:175], v[122:123], v[114:115]
	v_rcp_f32_e32 v152, v152
	v_rcp_f32_e32 v153, v153
; __device__ __forceinline__ unsigned cvt_pk_bf16(float lo, float hi) { unsigned r; asm volatile("v_cvt_pk_bf16_f32 %0, %1, %2" : "=v"(r) : "v"(lo), "v"(hi)); return r; }
; __device__ __forceinline__ float sigmoid_f(float x) { return __builtin_amdgcn_rcpf(1.0f + __builtin_amdgcn_exp2f(-1.4426950409f * x)); }
;     __device__ __forceinline__ void operator()(f32x4 (&acc)[2][2][4][2], const Unit& u, int wr, int wc, int fr, int fq) const {
;     ...
;                 for (int m = 0; m < 4; ++m) { bf16_t* rowp = O + (size_t)(row0 + ai * HALF + m * 16) * LDP + col0;
;                     float v[8];
; #pragma unroll
;                     for (int j = 0; j < 8; ++j) {
;                         const float x0 = acc[ai][0][m][j >> 2][j & 3], x1 = acc[ai][1][m][j >> 2][j & 3];
;                         const float f0 = (mode == 4) ? x0 * sigmoid_f(1.5957691216f * (x0 + 0.044715f * x0 * x0 * x0)) : x0;
;                         const float f1 = (mode == 5) ? x1 : x1 * sigmoid_f(x1);
;                         v[j] = f0 * f1;
;                     }
;                     u32x4 w; w.x = cvt_pk_bf16(v[0], v[1]); w.y = cvt_pk_bf16(v[2], v[3]); w.z = cvt_pk_bf16(v[4], v[5]); w.w = cvt_pk_bf16(v[6], v[7]);
;                     *(u32x4*)rowp = w; }
	v_rcp_f32_e32 v154, v154
	v_rcp_f32_e32 v155, v155
	v_rcp_f32_e32 v156, v156
	v_rcp_f32_e32 v157, v157
	v_rcp_f32_e32 v158, v158
	v_rcp_f32_e32 v159, v159
	s_nop 0
	v_pk_mul_f32 v[152:153], v[168:169], v[152:153]
	v_pk_mul_f32 v[154:155], v[170:171], v[154:155]
	v_pk_mul_f32 v[156:157], v[172:173], v[156:157]
	v_pk_mul_f32 v[158:159], v[174:175], v[158:159]
	v_cvt_pk_bf16_f32 v176, v152, v153
	v_cvt_pk_bf16_f32 v177, v154, v155
	v_cvt_pk_bf16_f32 v178, v156, v157
	v_cvt_pk_bf16_f32 v179, v158, v159
	global_store_dwordx4 v150, v[176:179], s[24:25]
	s_add_u32 s24, s24, 0x8000
	s_addc_u32 s25, s25, 0
	v_pk_mul_f32 v[152:153], v[108:109], v[108:109]
	v_pk_mul_f32 v[154:155], v[110:111], v[110:111]
	v_pk_mul_f32 v[156:157], v[104:105], v[104:105]
	v_pk_mul_f32 v[158:159], v[106:107], v[106:107]
	v_pk_mul_f32 v[168:169], v[100:101], s[62:63]
	v_pk_mul_f32 v[170:171], v[102:103], s[62:63]
	v_pk_mul_f32 v[172:173], v[96:97], s[62:63]
	v_pk_mul_f32 v[174:175], v[98:99], s[62:63]
	v_fmaak_f32 v152, v151, v152, 0xc0135761
	v_fmaak_f32 v153, v151, v153, 0xc0135761
	v_fmaak_f32 v154, v151, v154, 0xc0135761
	v_fmaak_f32 v155, v151, v155, 0xc0135761
	v_fmaak_f32 v156, v151, v156, 0xc0135761
	v_fmaak_f32 v157, v151, v157, 0xc0135761
	v_fmaak_f32 v158, v151, v158, 0xc0135761
	v_fmaak_f32 v159, v151, v159, 0xc0135761
	v_exp_f32_e32 v168, v168
	v_exp_f32_e32 v169, v169
	v_exp_f32_e32 v170, v170
	v_exp_f32_e32 v171, v171
	v_exp_f32_e32 v172, v172
	v_exp_f32_e32 v173, v173
	v_exp_f32_e32 v174, v174
	v_exp_f32_e32 v175, v175
	v_pk_mul_f32 v[152:153], v[108:109], v[152:153]
	v_pk_mul_f32 v[154:155], v[110:111], v[154:155]
	v_pk_mul_f32 v[156:157], v[104:105], v[156:157]
	v_pk_mul_f32 v[158:159], v[106:107], v[158:159]
	v_exp_f32_e32 v152, v152
	v_exp_f32_e32 v153, v153
	v_exp_f32_e32 v154, v154
	v_exp_f32_e32 v155, v155
	v_exp_f32_e32 v156, v156
	v_exp_f32_e32 v157, v157
	v_exp_f32_e32 v158, v158
	v_exp_f32_e32 v159, v159
	v_pk_add_f32 v[168:169], v[168:169], s[64:65]
	v_pk_add_f32 v[170:171], v[170:171], s[64:65]
	v_pk_add_f32 v[172:173], v[172:173], s[64:65]
	v_pk_add_f32 v[174:175], v[174:175], s[64:65]
	v_pk_fma_f32 v[152:153], v[152:153], v[168:169], v[168:169]
	v_pk_fma_f32 v[154:155], v[154:155], v[170:171], v[170:171]
	v_pk_fma_f32 v[156:157], v[156:157], v[172:173], v[172:173]
	v_pk_fma_f32 v[158:159], v[158:159], v[174:175], v[174:175]
	v_pk_mul_f32 v[168:169], v[108:109], v[100:101]
	v_pk_mul_f32 v[170:171], v[110:111], v[102:103]
	v_pk_mul_f32 v[172:173], v[104:105], v[96:97]
	v_pk_mul_f32 v[174:175], v[106:107], v[98:99]
	v_rcp_f32_e32 v152, v152
	v_rcp_f32_e32 v153, v153
	v_rcp_f32_e32 v154, v154
	v_rcp_f32_e32 v155, v155
	v_rcp_f32_e32 v156, v156
	v_rcp_f32_e32 v157, v157
	v_rcp_f32_e32 v158, v158
	v_rcp_f32_e32 v159, v159
	s_nop 0
	v_pk_mul_f32 v[152:153], v[168:169], v[152:153]
	v_pk_mul_f32 v[154:155], v[170:171], v[154:155]
	v_pk_mul_f32 v[156:157], v[172:173], v[156:157]
	v_pk_mul_f32 v[158:159], v[174:175], v[158:159]
	v_cvt_pk_bf16_f32 v180, v152, v153
	v_cvt_pk_bf16_f32 v181, v154, v155
	v_cvt_pk_bf16_f32 v182, v156, v157
	v_cvt_pk_bf16_f32 v183, v158, v159
	global_store_dwordx4 v150, v[180:183], s[24:25]
	s_add_u32 s24, s24, 0x8000
	s_addc_u32 s25, s25, 0
	v_pk_mul_f32 v[152:153], v[92:93], v[92:93]
	v_pk_mul_f32 v[154:155], v[94:95], v[94:95]
	v_pk_mul_f32 v[156:157], v[88:89], v[88:89]
	v_pk_mul_f32 v[158:159], v[90:91], v[90:91]
	v_pk_mul_f32 v[168:169], v[84:85], s[62:63]
	v_pk_mul_f32 v[170:171], v[86:87], s[62:63]
	v_pk_mul_f32 v[172:173], v[80:81], s[62:63]
	v_pk_mul_f32 v[174:175], v[82:83], s[62:63]
	v_fmaak_f32 v152, v151, v152, 0xc0135761
	v_fmaak_f32 v153, v151, v153, 0xc0135761
	v_fmaak_f32 v154, v151, v154, 0xc0135761
	v_fmaak_f32 v155, v151, v155, 0xc0135761
	v_fmaak_f32 v156, v151, v156, 0xc0135761
	v_fmaak_f32 v157, v151, v157, 0xc0135761
	v_fmaak_f32 v158, v151, v158, 0xc0135761
	v_fmaak_f32 v159, v151, v159, 0xc0135761
	v_exp_f32_e32 v168, v168
	v_exp_f32_e32 v169, v169
	v_exp_f32_e32 v170, v170
	v_exp_f32_e32 v171, v171
	v_exp_f32_e32 v172, v172
	v_exp_f32_e32 v173, v173
	v_exp_f32_e32 v174, v174
	v_exp_f32_e32 v175, v175
	v_pk_mul_f32 v[152:153], v[92:93], v[152:153]
	v_pk_mul_f32 v[154:155], v[94:95], v[154:155]
	v_pk_mul_f32 v[156:157], v[88:89], v[156:157]
	v_pk_mul_f32 v[158:159], v[90:91], v[158:159]
	v_exp_f32_e32 v152, v152
	v_exp_f32_e32 v153, v153
	v_exp_f32_e32 v154, v154
	v_exp_f32_e32 v155, v155
	v_exp_f32_e32 v156, v156
	v_exp_f32_e32 v157, v157
	v_exp_f32_e32 v158, v158
	v_exp_f32_e32 v159, v159
	v_pk_add_f32 v[168:169], v[168:169], s[64:65]
	v_pk_add_f32 v[170:171], v[170:171], s[64:65]
	v_pk_add_f32 v[172:173], v[172:173], s[64:65]
	v_pk_add_f32 v[174:175], v[174:175], s[64:65]
	v_pk_fma_f32 v[152:153], v[152:153], v[168:169], v[168:169]
	v_pk_fma_f32 v[154:155], v[154:155], v[170:171], v[170:171]
	v_pk_fma_f32 v[156:157], v[156:157], v[172:173], v[172:173]
	v_pk_fma_f32 v[158:159], v[158:159], v[174:175], v[174:175]
	v_pk_mul_f32 v[168:169], v[92:93], v[84:85]
	v_pk_mul_f32 v[170:171], v[94:95], v[86:87]
	v_pk_mul_f32 v[172:173], v[88:89], v[80:81]
	v_pk_mul_f32 v[174:175], v[90:91], v[82:83]
	v_rcp_f32_e32 v152, v152
	v_rcp_f32_e32 v153, v153
	v_rcp_f32_e32 v154, v154
	v_rcp_f32_e32 v155, v155
	v_rcp_f32_e32 v156, v156
	v_rcp_f32_e32 v157, v157
	v_rcp_f32_e32 v158, v158
	v_rcp_f32_e32 v159, v159
	s_nop 0
	v_pk_mul_f32 v[152:153], v[168:169], v[152:153]
	v_pk_mul_f32 v[154:155], v[170:171], v[154:155]
	v_pk_mul_f32 v[156:157], v[172:173], v[156:157]
	v_pk_mul_f32 v[158:159], v[174:175], v[158:159]
	v_cvt_pk_bf16_f32 v176, v152, v153
	v_cvt_pk_bf16_f32 v177, v154, v155
	v_cvt_pk_bf16_f32 v178, v156, v157
; __device__ __forceinline__ unsigned cvt_pk_bf16(float lo, float hi) { unsigned r; asm volatile("v_cvt_pk_bf16_f32 %0, %1, %2" : "=v"(r) : "v"(lo), "v"(hi)); return r; }
; __device__ __forceinline__ float sigmoid_f(float x) { return __builtin_amdgcn_rcpf(1.0f + __builtin_amdgcn_exp2f(-1.4426950409f * x)); }
;     __device__ __forceinline__ void operator()(f32x4 (&acc)[2][2][4][2], const Unit& u, int wr, int wc, int fr, int fq) const {
;     ...
;                 for (int m = 0; m < 4; ++m) { bf16_t* rowp = O + (size_t)(row0 + ai * HALF + m * 16) * LDP + col0;
;                     float v[8];
; #pragma unroll
;                     for (int j = 0; j < 8; ++j) {
;                         const float x0 = acc[ai][0][m][j >> 2][j & 3], x1 = acc[ai][1][m][j >> 2][j & 3];
;                         const float f0 = (mode == 4) ? x0 * sigmoid_f(1.5957691216f * (x0 + 0.044715f * x0 * x0 * x0)) : x0;
;                         const float f1 = (mode == 5) ? x1 : x1 * sigmoid_f(x1);
;                         v[j] = f0 * f1;
;                     }
;                     u32x4 w; w.x = cvt_pk_bf16(v[0], v[1]); w.y = cvt_pk_bf16(v[2], v[3]); w.z = cvt_pk_bf16(v[4], v[5]); w.w = cvt_pk_bf16(v[6], v[7]);
;                     *(u32x4*)rowp = w; }
	v_cvt_pk_bf16_f32 v179, v158, v159
	global_store_dwordx4 v150, v[176:179], s[24:25]
	s_add_u32 s24, s24, 0x8000
	s_addc_u32 s25, s25, 0
	v_pk_mul_f32 v[152:153], v[76:77], v[76:77]
	v_pk_mul_f32 v[154:155], v[78:79], v[78:79]
	v_pk_mul_f32 v[156:157], v[72:73], v[72:73]
	v_pk_mul_f32 v[158:159], v[74:75], v[74:75]
	v_pk_mul_f32 v[168:169], v[68:69], s[62:63]
	v_pk_mul_f32 v[170:171], v[70:71], s[62:63]
	v_pk_mul_f32 v[172:173], v[64:65], s[62:63]
	v_pk_mul_f32 v[174:175], v[66:67], s[62:63]
	v_fmaak_f32 v152, v151, v152, 0xc0135761
	v_fmaak_f32 v153, v151, v153, 0xc0135761
	v_fmaak_f32 v154, v151, v154, 0xc0135761
	v_fmaak_f32 v155, v151, v155, 0xc0135761
	v_fmaak_f32 v156, v151, v156, 0xc0135761
	v_fmaak_f32 v157, v151, v157, 0xc0135761
	v_fmaak_f32 v158, v151, v158, 0xc0135761
	v_fmaak_f32 v159, v151, v159, 0xc0135761
	v_exp_f32_e32 v168, v168
	v_exp_f32_e32 v169, v169
	v_exp_f32_e32 v170, v170
	v_exp_f32_e32 v171, v171
	v_exp_f32_e32 v172, v172
	v_exp_f32_e32 v173, v173
	v_exp_f32_e32 v174, v174
	v_exp_f32_e32 v175, v175
	v_pk_mul_f32 v[152:153], v[76:77], v[152:153]
	v_pk_mul_f32 v[154:155], v[78:79], v[154:155]
	v_pk_mul_f32 v[156:157], v[72:73], v[156:157]
	v_pk_mul_f32 v[158:159], v[74:75], v[158:159]
	v_exp_f32_e32 v152, v152
	v_exp_f32_e32 v153, v153
	v_exp_f32_e32 v154, v154
	v_exp_f32_e32 v155, v155
	v_exp_f32_e32 v156, v156
	v_exp_f32_e32 v157, v157
	v_exp_f32_e32 v158, v158
	v_exp_f32_e32 v159, v159
	v_pk_add_f32 v[168:169], v[168:169], s[64:65]
	v_pk_add_f32 v[170:171], v[170:171], s[64:65]
	v_pk_add_f32 v[172:173], v[172:173], s[64:65]
	v_pk_add_f32 v[174:175], v[174:175], s[64:65]
	v_pk_fma_f32 v[152:153], v[152:153], v[168:169], v[168:169]
	v_pk_fma_f32 v[154:155], v[154:155], v[170:171], v[170:171]
	v_pk_fma_f32 v[156:157], v[156:157], v[172:173], v[172:173]
	v_pk_fma_f32 v[158:159], v[158:159], v[174:175], v[174:175]
	v_pk_mul_f32 v[168:169], v[76:77], v[68:69]
	v_pk_mul_f32 v[170:171], v[78:79], v[70:71]
	v_pk_mul_f32 v[172:173], v[72:73], v[64:65]
	v_pk_mul_f32 v[174:175], v[74:75], v[66:67]
	v_rcp_f32_e32 v152, v152
	v_rcp_f32_e32 v153, v153
	v_rcp_f32_e32 v154, v154
	v_rcp_f32_e32 v155, v155
	v_rcp_f32_e32 v156, v156
	v_rcp_f32_e32 v157, v157
	v_rcp_f32_e32 v158, v158
	v_rcp_f32_e32 v159, v159
	s_nop 0
	v_pk_mul_f32 v[152:153], v[168:169], v[152:153]
	v_pk_mul_f32 v[154:155], v[170:171], v[154:155]
	v_pk_mul_f32 v[156:157], v[172:173], v[156:157]
	v_pk_mul_f32 v[158:159], v[174:175], v[158:159]
	v_cvt_pk_bf16_f32 v180, v152, v153
	v_cvt_pk_bf16_f32 v181, v154, v155
	v_cvt_pk_bf16_f32 v182, v156, v157
	v_cvt_pk_bf16_f32 v183, v158, v159
	global_store_dwordx4 v150, v[180:183], s[24:25]
	s_add_u32 s24, s24, 0x28000
	s_addc_u32 s25, s25, 0
	v_pk_mul_f32 v[152:153], v[60:61], v[60:61]
	v_pk_mul_f32 v[154:155], v[62:63], v[62:63]
	v_pk_mul_f32 v[156:157], v[56:57], v[56:57]
	v_pk_mul_f32 v[158:159], v[58:59], v[58:59]
	v_pk_mul_f32 v[168:169], v[52:53], s[62:63]
	v_pk_mul_f32 v[170:171], v[54:55], s[62:63]
	v_pk_mul_f32 v[172:173], v[48:49], s[62:63]
	v_pk_mul_f32 v[174:175], v[50:51], s[62:63]
	v_fmaak_f32 v152, v151, v152, 0xc0135761
	v_fmaak_f32 v153, v151, v153, 0xc0135761
	v_fmaak_f32 v154, v151, v154, 0xc0135761
	v_fmaak_f32 v155, v151, v155, 0xc0135761
	v_fmaak_f32 v156, v151, v156, 0xc0135761
	v_fmaak_f32 v157, v151, v157, 0xc0135761
	v_fmaak_f32 v158, v151, v158, 0xc0135761
	v_fmaak_f32 v159, v151, v159, 0xc0135761
	v_exp_f32_e32 v168, v168
	v_exp_f32_e32 v169, v169
	v_exp_f32_e32 v170, v170
	v_exp_f32_e32 v171, v171
	v_exp_f32_e32 v172, v172
	v_exp_f32_e32 v173, v173
	v_exp_f32_e32 v174, v174
	v_exp_f32_e32 v175, v175
	v_pk_mul_f32 v[152:153], v[60:61], v[152:153]
	v_pk_mul_f32 v[154:155], v[62:63], v[154:155]
	v_pk_mul_f32 v[156:157], v[56:57], v[156:157]
	v_pk_mul_f32 v[158:159], v[58:59], v[158:159]
	v_exp_f32_e32 v152, v152
	v_exp_f32_e32 v153, v153
	v_exp_f32_e32 v154, v154
	v_exp_f32_e32 v155, v155
	v_exp_f32_e32 v156, v156
	v_exp_f32_e32 v157, v157
	v_exp_f32_e32 v158, v158
	v_exp_f32_e32 v159, v159
	v_pk_add_f32 v[168:169], v[168:169], s[64:65]
	v_pk_add_f32 v[170:171], v[170:171], s[64:65]
	v_pk_add_f32 v[172:173], v[172:173], s[64:65]
	v_pk_add_f32 v[174:175], v[174:175], s[64:65]
	v_pk_fma_f32 v[152:153], v[152:153], v[168:169], v[168:169]
	v_pk_fma_f32 v[154:155], v[154:155], v[170:171], v[170:171]
	v_pk_fma_f32 v[156:157], v[156:157], v[172:173], v[172:173]
	v_pk_fma_f32 v[158:159], v[158:159], v[174:175], v[174:175]
	v_pk_mul_f32 v[168:169], v[60:61], v[52:53]
	v_pk_mul_f32 v[170:171], v[62:63], v[54:55]
	v_pk_mul_f32 v[172:173], v[56:57], v[48:49]
	v_pk_mul_f32 v[174:175], v[58:59], v[50:51]
	v_rcp_f32_e32 v152, v152
	v_rcp_f32_e32 v153, v153
	v_rcp_f32_e32 v154, v154
	v_rcp_f32_e32 v155, v155
	v_rcp_f32_e32 v156, v156
	v_rcp_f32_e32 v157, v157
	v_rcp_f32_e32 v158, v158
	v_rcp_f32_e32 v159, v159
	s_nop 0
	v_pk_mul_f32 v[152:153], v[168:169], v[152:153]
	v_pk_mul_f32 v[154:155], v[170:171], v[154:155]
	v_pk_mul_f32 v[156:157], v[172:173], v[156:157]
	v_pk_mul_f32 v[158:159], v[174:175], v[158:159]
	v_cvt_pk_bf16_f32 v176, v152, v153
	v_cvt_pk_bf16_f32 v177, v154, v155
	v_cvt_pk_bf16_f32 v178, v156, v157
	v_cvt_pk_bf16_f32 v179, v158, v159
	global_store_dwordx4 v150, v[176:179], s[24:25]
	s_add_u32 s24, s24, 0x8000
	s_addc_u32 s25, s25, 0
	v_pk_mul_f32 v[152:153], v[44:45], v[44:45]
	v_pk_mul_f32 v[154:155], v[46:47], v[46:47]
	v_pk_mul_f32 v[156:157], v[40:41], v[40:41]
	v_pk_mul_f32 v[158:159], v[42:43], v[42:43]
	v_pk_mul_f32 v[168:169], v[36:37], s[62:63]
	v_pk_mul_f32 v[170:171], v[38:39], s[62:63]
	v_pk_mul_f32 v[172:173], v[32:33], s[62:63]
	v_pk_mul_f32 v[174:175], v[34:35], s[62:63]
; __device__ __forceinline__ unsigned cvt_pk_bf16(float lo, float hi) { unsigned r; asm volatile("v_cvt_pk_bf16_f32 %0, %1, %2" : "=v"(r) : "v"(lo), "v"(hi)); return r; }
; __device__ __forceinline__ float sigmoid_f(float x) { return __builtin_amdgcn_rcpf(1.0f + __builtin_amdgcn_exp2f(-1.4426950409f * x)); }
;     __device__ __forceinline__ void operator()(f32x4 (&acc)[2][2][4][2], const Unit& u, int wr, int wc, int fr, int fq) const {
;     ...
;                 for (int m = 0; m < 4; ++m) { bf16_t* rowp = O + (size_t)(row0 + ai * HALF + m * 16) * LDP + col0;
;                     float v[8];
; #pragma unroll
;                     for (int j = 0; j < 8; ++j) {
;                         const float x0 = acc[ai][0][m][j >> 2][j & 3], x1 = acc[ai][1][m][j >> 2][j & 3];
;                         const float f0 = (mode == 4) ? x0 * sigmoid_f(1.5957691216f * (x0 + 0.044715f * x0 * x0 * x0)) : x0;
;                         const float f1 = (mode == 5) ? x1 : x1 * sigmoid_f(x1);
;                         v[j] = f0 * f1;
;                     }
;                     u32x4 w; w.x = cvt_pk_bf16(v[0], v[1]); w.y = cvt_pk_bf16(v[2], v[3]); w.z = cvt_pk_bf16(v[4], v[5]); w.w = cvt_pk_bf16(v[6], v[7]);
;                     *(u32x4*)rowp = w; }
	v_fmaak_f32 v152, v151, v152, 0xc0135761
	v_fmaak_f32 v153, v151, v153, 0xc0135761
	v_fmaak_f32 v154, v151, v154, 0xc0135761
	v_fmaak_f32 v155, v151, v155, 0xc0135761
	v_fmaak_f32 v156, v151, v156, 0xc0135761
	v_fmaak_f32 v157, v151, v157, 0xc0135761
	v_fmaak_f32 v158, v151, v158, 0xc0135761
	v_fmaak_f32 v159, v151, v159, 0xc0135761
	v_exp_f32_e32 v168, v168
	v_exp_f32_e32 v169, v169
	v_exp_f32_e32 v170, v170
	v_exp_f32_e32 v171, v171
	v_exp_f32_e32 v172, v172
	v_exp_f32_e32 v173, v173
	v_exp_f32_e32 v174, v174
	v_exp_f32_e32 v175, v175
	v_pk_mul_f32 v[152:153], v[44:45], v[152:153]
	v_pk_mul_f32 v[154:155], v[46:47], v[154:155]
	v_pk_mul_f32 v[156:157], v[40:41], v[156:157]
	v_pk_mul_f32 v[158:159], v[42:43], v[158:159]
	v_exp_f32_e32 v152, v152
	v_exp_f32_e32 v153, v153
	v_exp_f32_e32 v154, v154
	v_exp_f32_e32 v155, v155
	v_exp_f32_e32 v156, v156
	v_exp_f32_e32 v157, v157
	v_exp_f32_e32 v158, v158
	v_exp_f32_e32 v159, v159
	v_pk_add_f32 v[168:169], v[168:169], s[64:65]
	v_pk_add_f32 v[170:171], v[170:171], s[64:65]
	v_pk_add_f32 v[172:173], v[172:173], s[64:65]
	v_pk_add_f32 v[174:175], v[174:175], s[64:65]
	v_pk_fma_f32 v[152:153], v[152:153], v[168:169], v[168:169]
	v_pk_fma_f32 v[154:155], v[154:155], v[170:171], v[170:171]
	v_pk_fma_f32 v[156:157], v[156:157], v[172:173], v[172:173]
	v_pk_fma_f32 v[158:159], v[158:159], v[174:175], v[174:175]
	v_pk_mul_f32 v[168:169], v[44:45], v[36:37]
	v_pk_mul_f32 v[170:171], v[46:47], v[38:39]
	v_pk_mul_f32 v[172:173], v[40:41], v[32:33]
	v_pk_mul_f32 v[174:175], v[42:43], v[34:35]
	v_rcp_f32_e32 v152, v152
	v_rcp_f32_e32 v153, v153
	v_rcp_f32_e32 v154, v154
	v_rcp_f32_e32 v155, v155
	v_rcp_f32_e32 v156, v156
	v_rcp_f32_e32 v157, v157
	v_rcp_f32_e32 v158, v158
	v_rcp_f32_e32 v159, v159
	s_nop 0
	v_pk_mul_f32 v[152:153], v[168:169], v[152:153]
	v_pk_mul_f32 v[154:155], v[170:171], v[154:155]
	v_pk_mul_f32 v[156:157], v[172:173], v[156:157]
	v_pk_mul_f32 v[158:159], v[174:175], v[158:159]
	v_cvt_pk_bf16_f32 v180, v152, v153
	v_cvt_pk_bf16_f32 v181, v154, v155
	v_cvt_pk_bf16_f32 v182, v156, v157
	v_cvt_pk_bf16_f32 v183, v158, v159
	global_store_dwordx4 v150, v[180:183], s[24:25]
	s_add_u32 s24, s24, 0x8000
	s_addc_u32 s25, s25, 0
	v_pk_mul_f32 v[152:153], v[28:29], v[28:29]
	v_pk_mul_f32 v[154:155], v[30:31], v[30:31]
	v_pk_mul_f32 v[156:157], v[24:25], v[24:25]
	v_pk_mul_f32 v[158:159], v[26:27], v[26:27]
	v_pk_mul_f32 v[168:169], v[20:21], s[62:63]
	v_pk_mul_f32 v[170:171], v[22:23], s[62:63]
	v_pk_mul_f32 v[172:173], v[16:17], s[62:63]
	v_pk_mul_f32 v[174:175], v[18:19], s[62:63]
	v_fmaak_f32 v152, v151, v152, 0xc0135761
	v_fmaak_f32 v153, v151, v153, 0xc0135761
	v_fmaak_f32 v154, v151, v154, 0xc0135761
	v_fmaak_f32 v155, v151, v155, 0xc0135761
	v_fmaak_f32 v156, v151, v156, 0xc0135761
	v_fmaak_f32 v157, v151, v157, 0xc0135761
	v_fmaak_f32 v158, v151, v158, 0xc0135761
	v_fmaak_f32 v159, v151, v159, 0xc0135761
	v_exp_f32_e32 v168, v168
	v_exp_f32_e32 v169, v169
	v_exp_f32_e32 v170, v170
	v_exp_f32_e32 v171, v171
	v_exp_f32_e32 v172, v172
	v_exp_f32_e32 v173, v173
	v_exp_f32_e32 v174, v174
	v_exp_f32_e32 v175, v175
	v_pk_mul_f32 v[152:153], v[28:29], v[152:153]
	v_pk_mul_f32 v[154:155], v[30:31], v[154:155]
	v_pk_mul_f32 v[156:157], v[24:25], v[156:157]
	v_pk_mul_f32 v[158:159], v[26:27], v[158:159]
	v_exp_f32_e32 v152, v152
	v_exp_f32_e32 v153, v153
	v_exp_f32_e32 v154, v154
	v_exp_f32_e32 v155, v155
	v_exp_f32_e32 v156, v156
	v_exp_f32_e32 v157, v157
	v_exp_f32_e32 v158, v158
	v_exp_f32_e32 v159, v159
	v_pk_add_f32 v[168:169], v[168:169], s[64:65]
	v_pk_add_f32 v[170:171], v[170:171], s[64:65]
	v_pk_add_f32 v[172:173], v[172:173], s[64:65]
	v_pk_add_f32 v[174:175], v[174:175], s[64:65]
	v_pk_fma_f32 v[152:153], v[152:153], v[168:169], v[168:169]
	v_pk_fma_f32 v[154:155], v[154:155], v[170:171], v[170:171]
	v_pk_fma_f32 v[156:157], v[156:157], v[172:173], v[172:173]
	v_pk_fma_f32 v[158:159], v[158:159], v[174:175], v[174:175]
	v_pk_mul_f32 v[168:169], v[28:29], v[20:21]
	v_pk_mul_f32 v[170:171], v[30:31], v[22:23]
	v_pk_mul_f32 v[172:173], v[24:25], v[16:17]
	v_pk_mul_f32 v[174:175], v[26:27], v[18:19]
	v_rcp_f32_e32 v152, v152
	v_rcp_f32_e32 v153, v153
	v_rcp_f32_e32 v154, v154
	v_rcp_f32_e32 v155, v155
	v_rcp_f32_e32 v156, v156
	v_rcp_f32_e32 v157, v157
	v_rcp_f32_e32 v158, v158
	v_rcp_f32_e32 v159, v159
	s_nop 0
	v_pk_mul_f32 v[152:153], v[168:169], v[152:153]
	v_pk_mul_f32 v[154:155], v[170:171], v[154:155]
	v_pk_mul_f32 v[156:157], v[172:173], v[156:157]
	v_pk_mul_f32 v[158:159], v[174:175], v[158:159]
	v_cvt_pk_bf16_f32 v176, v152, v153
	v_cvt_pk_bf16_f32 v177, v154, v155
	v_cvt_pk_bf16_f32 v178, v156, v157
	v_cvt_pk_bf16_f32 v179, v158, v159
	global_store_dwordx4 v150, v[176:179], s[24:25]
	s_add_u32 s24, s24, 0x8000
	s_addc_u32 s25, s25, 0
	v_pk_mul_f32 v[152:153], v[12:13], v[12:13]
	v_pk_mul_f32 v[154:155], v[14:15], v[14:15]
	v_pk_mul_f32 v[156:157], v[8:9], v[8:9]
	v_pk_mul_f32 v[158:159], v[10:11], v[10:11]
	v_pk_mul_f32 v[168:169], v[4:5], s[62:63]
	v_pk_mul_f32 v[170:171], v[6:7], s[62:63]
	v_pk_mul_f32 v[172:173], v[0:1], s[62:63]
	v_pk_mul_f32 v[174:175], v[2:3], s[62:63]
	v_fmaak_f32 v152, v151, v152, 0xc0135761
	v_fmaak_f32 v153, v151, v153, 0xc0135761
	v_fmaak_f32 v154, v151, v154, 0xc0135761
	v_fmaak_f32 v155, v151, v155, 0xc0135761
	v_fmaak_f32 v156, v151, v156, 0xc0135761
	v_fmaak_f32 v157, v151, v157, 0xc0135761
	v_fmaak_f32 v158, v151, v158, 0xc0135761
	v_fmaak_f32 v159, v151, v159, 0xc0135761
	v_exp_f32_e32 v168, v168
	v_exp_f32_e32 v169, v169
	v_exp_f32_e32 v170, v170
	v_exp_f32_e32 v171, v171
	v_exp_f32_e32 v172, v172
	v_exp_f32_e32 v173, v173
	v_exp_f32_e32 v174, v174
; __device__ __forceinline__ unsigned cvt_pk_bf16(float lo, float hi) { unsigned r; asm volatile("v_cvt_pk_bf16_f32 %0, %1, %2" : "=v"(r) : "v"(lo), "v"(hi)); return r; }
; __device__ __forceinline__ float sigmoid_f(float x) { return __builtin_amdgcn_rcpf(1.0f + __builtin_amdgcn_exp2f(-1.4426950409f * x)); }
;     __device__ __forceinline__ void operator()(f32x4 (&acc)[2][2][4][2], const Unit& u, int wr, int wc, int fr, int fq) const {
;     ...
;                 for (int m = 0; m < 4; ++m) { bf16_t* rowp = O + (size_t)(row0 + ai * HALF + m * 16) * LDP + col0;
;                     float v[8];
; #pragma unroll
;                     for (int j = 0; j < 8; ++j) {
;                         const float x0 = acc[ai][0][m][j >> 2][j & 3], x1 = acc[ai][1][m][j >> 2][j & 3];
;                         const float f0 = (mode == 4) ? x0 * sigmoid_f(1.5957691216f * (x0 + 0.044715f * x0 * x0 * x0)) : x0;
;                         const float f1 = (mode == 5) ? x1 : x1 * sigmoid_f(x1);
;                         v[j] = f0 * f1;
;                     }
;                     u32x4 w; w.x = cvt_pk_bf16(v[0], v[1]); w.y = cvt_pk_bf16(v[2], v[3]); w.z = cvt_pk_bf16(v[4], v[5]); w.w = cvt_pk_bf16(v[6], v[7]);
;                     *(u32x4*)rowp = w; }
;     ...
;                 for (int m = 0; m < 4; ++m) { bf16_t* rowp = O + (size_t)(row0 + ai * HALF + m * 16) * LDP + col0;
; #pragma unroll
;                     for (int bj = 0; bj < 2; ++bj) {
;                         float v[8];
; #pragma unroll
;                         for (int j = 0; j < 4; ++j) { v[j] = acc[ai][bj][m][0][j]; v[4 + j] = acc[ai][bj][m][1][j]; }
;                         if (mode != 0) {
; #pragma unroll
;                             for (int j = 0; j < 8; ++j) {
;                                 const float x = v[j];
;                                 const float a = (mode == 1) ? 1.5957691216f * (x + 0.044715f * x * x * x) : x;
;                                 const float sg = sigmoid_f(a);
;                                 v[j] = (mode == 3) ? sg : x * sg;
;                             }
;                         }
;                         u32x4 w; w.x = cvt_pk_bf16(v[0], v[1]); w.y = cvt_pk_bf16(v[2], v[3]); w.z = cvt_pk_bf16(v[4], v[5]); w.w = cvt_pk_bf16(v[6], v[7]);
;                         *(u32x4*)(rowp + bj * HALF) = w; } }
	v_exp_f32_e32 v175, v175
	v_pk_mul_f32 v[152:153], v[12:13], v[152:153]
	v_pk_mul_f32 v[154:155], v[14:15], v[154:155]
	v_pk_mul_f32 v[156:157], v[8:9], v[156:157]
	v_pk_mul_f32 v[158:159], v[10:11], v[158:159]
	v_exp_f32_e32 v152, v152
	v_exp_f32_e32 v153, v153
	v_exp_f32_e32 v154, v154
	v_exp_f32_e32 v155, v155
	v_exp_f32_e32 v156, v156
	v_exp_f32_e32 v157, v157
	v_exp_f32_e32 v158, v158
	v_exp_f32_e32 v159, v159
	v_pk_add_f32 v[168:169], v[168:169], s[64:65]
	v_pk_add_f32 v[170:171], v[170:171], s[64:65]
	v_pk_add_f32 v[172:173], v[172:173], s[64:65]
	v_pk_add_f32 v[174:175], v[174:175], s[64:65]
	v_pk_fma_f32 v[152:153], v[152:153], v[168:169], v[168:169]
	v_pk_fma_f32 v[154:155], v[154:155], v[170:171], v[170:171]
	v_pk_fma_f32 v[156:157], v[156:157], v[172:173], v[172:173]
	v_pk_fma_f32 v[158:159], v[158:159], v[174:175], v[174:175]
	v_pk_mul_f32 v[168:169], v[12:13], v[4:5]
	v_pk_mul_f32 v[170:171], v[14:15], v[6:7]
	v_pk_mul_f32 v[172:173], v[8:9], v[0:1]
	v_pk_mul_f32 v[174:175], v[10:11], v[2:3]
	v_rcp_f32_e32 v152, v152
	v_rcp_f32_e32 v153, v153
	v_rcp_f32_e32 v154, v154
	v_rcp_f32_e32 v155, v155
	v_rcp_f32_e32 v156, v156
	v_rcp_f32_e32 v157, v157
	v_rcp_f32_e32 v158, v158
	v_rcp_f32_e32 v159, v159
	s_nop 0
	v_pk_mul_f32 v[152:153], v[168:169], v[152:153]
	v_pk_mul_f32 v[154:155], v[170:171], v[154:155]
	v_pk_mul_f32 v[156:157], v[172:173], v[156:157]
	v_pk_mul_f32 v[158:159], v[174:175], v[158:159]
	v_cvt_pk_bf16_f32 v180, v152, v153
	v_cvt_pk_bf16_f32 v181, v154, v155
	v_cvt_pk_bf16_f32 v182, v156, v157
	v_cvt_pk_bf16_f32 v183, v158, v159
	global_store_dwordx4 v150, v[180:183], s[24:25]
	s_branch .LBB0_298
.Lp1_epi_m1:
	s_lshl_b32 s14, s59, 9
	s_add_u32 s14, s14, 0x3fff000
	s_add_u32 s24, s24, s14
	s_addc_u32 s25, s25, 0
	v_mov_b32_e32 v151, 0xbdd2d3e8
	v_pk_mul_f32 v[152:153], v[124:125], v[124:125]
	v_pk_mul_f32 v[154:155], v[126:127], v[126:127]
	v_pk_mul_f32 v[156:157], v[120:121], v[120:121]
	v_pk_mul_f32 v[158:159], v[122:123], v[122:123]
	v_fmaak_f32 v152, v151, v152, 0xc0135761
	v_fmaak_f32 v153, v151, v153, 0xc0135761
	v_fmaak_f32 v154, v151, v154, 0xc0135761
	v_fmaak_f32 v155, v151, v155, 0xc0135761
	v_fmaak_f32 v156, v151, v156, 0xc0135761
	v_fmaak_f32 v157, v151, v157, 0xc0135761
	v_fmaak_f32 v158, v151, v158, 0xc0135761
	v_fmaak_f32 v159, v151, v159, 0xc0135761
	v_pk_mul_f32 v[152:153], v[124:125], v[152:153]
	v_pk_mul_f32 v[154:155], v[126:127], v[154:155]
	v_pk_mul_f32 v[156:157], v[120:121], v[156:157]
	v_pk_mul_f32 v[158:159], v[122:123], v[158:159]
	v_exp_f32_e32 v152, v152
	v_exp_f32_e32 v153, v153
	v_exp_f32_e32 v154, v154
	v_exp_f32_e32 v155, v155
	v_exp_f32_e32 v156, v156
	v_exp_f32_e32 v157, v157
	v_exp_f32_e32 v158, v158
	v_exp_f32_e32 v159, v159
	s_nop 0
	v_pk_add_f32 v[152:153], v[152:153], s[64:65]
	v_pk_add_f32 v[154:155], v[154:155], s[64:65]
	v_pk_add_f32 v[156:157], v[156:157], s[64:65]
	v_pk_add_f32 v[158:159], v[158:159], s[64:65]
	v_rcp_f32_e32 v152, v152
	v_rcp_f32_e32 v153, v153
	v_rcp_f32_e32 v154, v154
	v_rcp_f32_e32 v155, v155
	v_rcp_f32_e32 v156, v156
	v_rcp_f32_e32 v157, v157
	v_rcp_f32_e32 v158, v158
	v_rcp_f32_e32 v159, v159
	s_nop 0
	v_pk_mul_f32 v[152:153], v[124:125], v[152:153]
	v_pk_mul_f32 v[154:155], v[126:127], v[154:155]
	v_pk_mul_f32 v[156:157], v[120:121], v[156:157]
	v_pk_mul_f32 v[158:159], v[122:123], v[158:159]
	v_cvt_pk_bf16_f32 v176, v152, v153
	v_cvt_pk_bf16_f32 v177, v154, v155
	v_cvt_pk_bf16_f32 v178, v156, v157
	v_cvt_pk_bf16_f32 v179, v158, v159
	global_store_dwordx4 v150, v[176:179], s[24:25]
	v_pk_mul_f32 v[152:153], v[116:117], v[116:117]
	v_pk_mul_f32 v[154:155], v[118:119], v[118:119]
	v_pk_mul_f32 v[156:157], v[112:113], v[112:113]
	v_pk_mul_f32 v[158:159], v[114:115], v[114:115]
	v_fmaak_f32 v152, v151, v152, 0xc0135761
	v_fmaak_f32 v153, v151, v153, 0xc0135761
	v_fmaak_f32 v154, v151, v154, 0xc0135761
	v_fmaak_f32 v155, v151, v155, 0xc0135761
	v_fmaak_f32 v156, v151, v156, 0xc0135761
	v_fmaak_f32 v157, v151, v157, 0xc0135761
	v_fmaak_f32 v158, v151, v158, 0xc0135761
	v_fmaak_f32 v159, v151, v159, 0xc0135761
	v_pk_mul_f32 v[152:153], v[116:117], v[152:153]
	v_pk_mul_f32 v[154:155], v[118:119], v[154:155]
	v_pk_mul_f32 v[156:157], v[112:113], v[156:157]
	v_pk_mul_f32 v[158:159], v[114:115], v[158:159]
	v_exp_f32_e32 v152, v152
	v_exp_f32_e32 v153, v153
	v_exp_f32_e32 v154, v154
	v_exp_f32_e32 v155, v155
	v_exp_f32_e32 v156, v156
	v_exp_f32_e32 v157, v157
	v_exp_f32_e32 v158, v158
	v_exp_f32_e32 v159, v159
	s_nop 0
	v_pk_add_f32 v[152:153], v[152:153], s[64:65]
	v_pk_add_f32 v[154:155], v[154:155], s[64:65]
	v_pk_add_f32 v[156:157], v[156:157], s[64:65]
	v_pk_add_f32 v[158:159], v[158:159], s[64:65]
	v_rcp_f32_e32 v152, v152
	v_rcp_f32_e32 v153, v153
	v_rcp_f32_e32 v154, v154
	v_rcp_f32_e32 v155, v155
	v_rcp_f32_e32 v156, v156
	v_rcp_f32_e32 v157, v157
	v_rcp_f32_e32 v158, v158
	v_rcp_f32_e32 v159, v159
	s_nop 0
	v_pk_mul_f32 v[152:153], v[116:117], v[152:153]
	v_pk_mul_f32 v[154:155], v[118:119], v[154:155]
	v_pk_mul_f32 v[156:157], v[112:113], v[156:157]
	v_pk_mul_f32 v[158:159], v[114:115], v[158:159]
	v_cvt_pk_bf16_f32 v180, v152, v153
	v_cvt_pk_bf16_f32 v181, v154, v155
	v_cvt_pk_bf16_f32 v182, v156, v157
	v_cvt_pk_bf16_f32 v183, v158, v159
	global_store_dwordx4 v150, v[180:183], s[24:25] offset:256
	s_add_u32 s24, s24, 0x8000
	s_addc_u32 s25, s25, 0
	v_pk_mul_f32 v[152:153], v[108:109], v[108:109]
	v_pk_mul_f32 v[154:155], v[110:111], v[110:111]
	v_pk_mul_f32 v[156:157], v[104:105], v[104:105]
	v_pk_mul_f32 v[158:159], v[106:107], v[106:107]
	v_fmaak_f32 v152, v151, v152, 0xc0135761
	v_fmaak_f32 v153, v151, v153, 0xc0135761
	v_fmaak_f32 v154, v151, v154, 0xc0135761
; __device__ __forceinline__ unsigned cvt_pk_bf16(float lo, float hi) { unsigned r; asm volatile("v_cvt_pk_bf16_f32 %0, %1, %2" : "=v"(r) : "v"(lo), "v"(hi)); return r; }
; __device__ __forceinline__ float sigmoid_f(float x) { return __builtin_amdgcn_rcpf(1.0f + __builtin_amdgcn_exp2f(-1.4426950409f * x)); }
;     __device__ __forceinline__ void operator()(f32x4 (&acc)[2][2][4][2], const Unit& u, int wr, int wc, int fr, int fq) const {
;     ...
;                 for (int m = 0; m < 4; ++m) { bf16_t* rowp = O + (size_t)(row0 + ai * HALF + m * 16) * LDP + col0;
; #pragma unroll
;                     for (int bj = 0; bj < 2; ++bj) {
;                         float v[8];
; #pragma unroll
;                         for (int j = 0; j < 4; ++j) { v[j] = acc[ai][bj][m][0][j]; v[4 + j] = acc[ai][bj][m][1][j]; }
;                         if (mode != 0) {
; #pragma unroll
;                             for (int j = 0; j < 8; ++j) {
;                                 const float x = v[j];
;                                 const float a = (mode == 1) ? 1.5957691216f * (x + 0.044715f * x * x * x) : x;
;                                 const float sg = sigmoid_f(a);
;                                 v[j] = (mode == 3) ? sg : x * sg;
;                             }
;                         }
;                         u32x4 w; w.x = cvt_pk_bf16(v[0], v[1]); w.y = cvt_pk_bf16(v[2], v[3]); w.z = cvt_pk_bf16(v[4], v[5]); w.w = cvt_pk_bf16(v[6], v[7]);
;                         *(u32x4*)(rowp + bj * HALF) = w; } }
	v_fmaak_f32 v155, v151, v155, 0xc0135761
	v_fmaak_f32 v156, v151, v156, 0xc0135761
	v_fmaak_f32 v157, v151, v157, 0xc0135761
	v_fmaak_f32 v158, v151, v158, 0xc0135761
	v_fmaak_f32 v159, v151, v159, 0xc0135761
	v_pk_mul_f32 v[152:153], v[108:109], v[152:153]
	v_pk_mul_f32 v[154:155], v[110:111], v[154:155]
	v_pk_mul_f32 v[156:157], v[104:105], v[156:157]
	v_pk_mul_f32 v[158:159], v[106:107], v[158:159]
	v_exp_f32_e32 v152, v152
	v_exp_f32_e32 v153, v153
	v_exp_f32_e32 v154, v154
	v_exp_f32_e32 v155, v155
	v_exp_f32_e32 v156, v156
	v_exp_f32_e32 v157, v157
	v_exp_f32_e32 v158, v158
	v_exp_f32_e32 v159, v159
	s_nop 0
	v_pk_add_f32 v[152:153], v[152:153], s[64:65]
	v_pk_add_f32 v[154:155], v[154:155], s[64:65]
	v_pk_add_f32 v[156:157], v[156:157], s[64:65]
	v_pk_add_f32 v[158:159], v[158:159], s[64:65]
	v_rcp_f32_e32 v152, v152
	v_rcp_f32_e32 v153, v153
	v_rcp_f32_e32 v154, v154
	v_rcp_f32_e32 v155, v155
	v_rcp_f32_e32 v156, v156
	v_rcp_f32_e32 v157, v157
	v_rcp_f32_e32 v158, v158
	v_rcp_f32_e32 v159, v159
	s_nop 0
	v_pk_mul_f32 v[152:153], v[108:109], v[152:153]
	v_pk_mul_f32 v[154:155], v[110:111], v[154:155]
	v_pk_mul_f32 v[156:157], v[104:105], v[156:157]
	v_pk_mul_f32 v[158:159], v[106:107], v[158:159]
	v_cvt_pk_bf16_f32 v176, v152, v153
	v_cvt_pk_bf16_f32 v177, v154, v155
	v_cvt_pk_bf16_f32 v178, v156, v157
	v_cvt_pk_bf16_f32 v179, v158, v159
	global_store_dwordx4 v150, v[176:179], s[24:25]
	v_pk_mul_f32 v[152:153], v[100:101], v[100:101]
	v_pk_mul_f32 v[154:155], v[102:103], v[102:103]
	v_pk_mul_f32 v[156:157], v[96:97], v[96:97]
	v_pk_mul_f32 v[158:159], v[98:99], v[98:99]
	v_fmaak_f32 v152, v151, v152, 0xc0135761
	v_fmaak_f32 v153, v151, v153, 0xc0135761
	v_fmaak_f32 v154, v151, v154, 0xc0135761
	v_fmaak_f32 v155, v151, v155, 0xc0135761
	v_fmaak_f32 v156, v151, v156, 0xc0135761
	v_fmaak_f32 v157, v151, v157, 0xc0135761
	v_fmaak_f32 v158, v151, v158, 0xc0135761
	v_fmaak_f32 v159, v151, v159, 0xc0135761
	v_pk_mul_f32 v[152:153], v[100:101], v[152:153]
	v_pk_mul_f32 v[154:155], v[102:103], v[154:155]
	v_pk_mul_f32 v[156:157], v[96:97], v[156:157]
	v_pk_mul_f32 v[158:159], v[98:99], v[158:159]
	v_exp_f32_e32 v152, v152
	v_exp_f32_e32 v153, v153
	v_exp_f32_e32 v154, v154
	v_exp_f32_e32 v155, v155
	v_exp_f32_e32 v156, v156
	v_exp_f32_e32 v157, v157
	v_exp_f32_e32 v158, v158
	v_exp_f32_e32 v159, v159
	s_nop 0
	v_pk_add_f32 v[152:153], v[152:153], s[64:65]
	v_pk_add_f32 v[154:155], v[154:155], s[64:65]
	v_pk_add_f32 v[156:157], v[156:157], s[64:65]
	v_pk_add_f32 v[158:159], v[158:159], s[64:65]
	v_rcp_f32_e32 v152, v152
	v_rcp_f32_e32 v153, v153
	v_rcp_f32_e32 v154, v154
	v_rcp_f32_e32 v155, v155
	v_rcp_f32_e32 v156, v156
	v_rcp_f32_e32 v157, v157
	v_rcp_f32_e32 v158, v158
	v_rcp_f32_e32 v159, v159
	s_nop 0
	v_pk_mul_f32 v[152:153], v[100:101], v[152:153]
	v_pk_mul_f32 v[154:155], v[102:103], v[154:155]
	v_pk_mul_f32 v[156:157], v[96:97], v[156:157]
	v_pk_mul_f32 v[158:159], v[98:99], v[158:159]
	v_cvt_pk_bf16_f32 v180, v152, v153
	v_cvt_pk_bf16_f32 v181, v154, v155
	v_cvt_pk_bf16_f32 v182, v156, v157
	v_cvt_pk_bf16_f32 v183, v158, v159
	global_store_dwordx4 v150, v[180:183], s[24:25] offset:256
	s_add_u32 s24, s24, 0x8000
	s_addc_u32 s25, s25, 0
	v_pk_mul_f32 v[152:153], v[92:93], v[92:93]
	v_pk_mul_f32 v[154:155], v[94:95], v[94:95]
	v_pk_mul_f32 v[156:157], v[88:89], v[88:89]
	v_pk_mul_f32 v[158:159], v[90:91], v[90:91]
	v_fmaak_f32 v152, v151, v152, 0xc0135761
	v_fmaak_f32 v153, v151, v153, 0xc0135761
	v_fmaak_f32 v154, v151, v154, 0xc0135761
	v_fmaak_f32 v155, v151, v155, 0xc0135761
	v_fmaak_f32 v156, v151, v156, 0xc0135761
	v_fmaak_f32 v157, v151, v157, 0xc0135761
	v_fmaak_f32 v158, v151, v158, 0xc0135761
	v_fmaak_f32 v159, v151, v159, 0xc0135761
	v_pk_mul_f32 v[152:153], v[92:93], v[152:153]
	v_pk_mul_f32 v[154:155], v[94:95], v[154:155]
	v_pk_mul_f32 v[156:157], v[88:89], v[156:157]
	v_pk_mul_f32 v[158:159], v[90:91], v[158:159]
	v_exp_f32_e32 v152, v152
	v_exp_f32_e32 v153, v153
	v_exp_f32_e32 v154, v154
	v_exp_f32_e32 v155, v155
	v_exp_f32_e32 v156, v156
	v_exp_f32_e32 v157, v157
	v_exp_f32_e32 v158, v158
	v_exp_f32_e32 v159, v159
	s_nop 0
	v_pk_add_f32 v[152:153], v[152:153], s[64:65]
	v_pk_add_f32 v[154:155], v[154:155], s[64:65]
	v_pk_add_f32 v[156:157], v[156:157], s[64:65]
	v_pk_add_f32 v[158:159], v[158:159], s[64:65]
	v_rcp_f32_e32 v152, v152
	v_rcp_f32_e32 v153, v153
	v_rcp_f32_e32 v154, v154
	v_rcp_f32_e32 v155, v155
	v_rcp_f32_e32 v156, v156
	v_rcp_f32_e32 v157, v157
	v_rcp_f32_e32 v158, v158
	v_rcp_f32_e32 v159, v159
	s_nop 0
	v_pk_mul_f32 v[152:153], v[92:93], v[152:153]
	v_pk_mul_f32 v[154:155], v[94:95], v[154:155]
	v_pk_mul_f32 v[156:157], v[88:89], v[156:157]
	v_pk_mul_f32 v[158:159], v[90:91], v[158:159]
	v_cvt_pk_bf16_f32 v176, v152, v153
	v_cvt_pk_bf16_f32 v177, v154, v155
	v_cvt_pk_bf16_f32 v178, v156, v157
	v_cvt_pk_bf16_f32 v179, v158, v159
	global_store_dwordx4 v150, v[176:179], s[24:25]
	v_pk_mul_f32 v[152:153], v[84:85], v[84:85]
	v_pk_mul_f32 v[154:155], v[86:87], v[86:87]
	v_pk_mul_f32 v[156:157], v[80:81], v[80:81]
	v_pk_mul_f32 v[158:159], v[82:83], v[82:83]
	v_fmaak_f32 v152, v151, v152, 0xc0135761
	v_fmaak_f32 v153, v151, v153, 0xc0135761
	v_fmaak_f32 v154, v151, v154, 0xc0135761
	v_fmaak_f32 v155, v151, v155, 0xc0135761
	v_fmaak_f32 v156, v151, v156, 0xc0135761
	v_fmaak_f32 v157, v151, v157, 0xc0135761
	v_fmaak_f32 v158, v151, v158, 0xc0135761
	v_fmaak_f32 v159, v151, v159, 0xc0135761
	v_pk_mul_f32 v[152:153], v[84:85], v[152:153]
	v_pk_mul_f32 v[154:155], v[86:87], v[154:155]
	v_pk_mul_f32 v[156:157], v[80:81], v[156:157]
	v_pk_mul_f32 v[158:159], v[82:83], v[158:159]
	v_exp_f32_e32 v152, v152
; __device__ __forceinline__ unsigned cvt_pk_bf16(float lo, float hi) { unsigned r; asm volatile("v_cvt_pk_bf16_f32 %0, %1, %2" : "=v"(r) : "v"(lo), "v"(hi)); return r; }
; __device__ __forceinline__ float sigmoid_f(float x) { return __builtin_amdgcn_rcpf(1.0f + __builtin_amdgcn_exp2f(-1.4426950409f * x)); }
;     __device__ __forceinline__ void operator()(f32x4 (&acc)[2][2][4][2], const Unit& u, int wr, int wc, int fr, int fq) const {
;     ...
;                 for (int m = 0; m < 4; ++m) { bf16_t* rowp = O + (size_t)(row0 + ai * HALF + m * 16) * LDP + col0;
; #pragma unroll
;                     for (int bj = 0; bj < 2; ++bj) {
;                         float v[8];
; #pragma unroll
;                         for (int j = 0; j < 4; ++j) { v[j] = acc[ai][bj][m][0][j]; v[4 + j] = acc[ai][bj][m][1][j]; }
;                         if (mode != 0) {
; #pragma unroll
;                             for (int j = 0; j < 8; ++j) {
;                                 const float x = v[j];
;                                 const float a = (mode == 1) ? 1.5957691216f * (x + 0.044715f * x * x * x) : x;
;                                 const float sg = sigmoid_f(a);
;                                 v[j] = (mode == 3) ? sg : x * sg;
;                             }
;                         }
;                         u32x4 w; w.x = cvt_pk_bf16(v[0], v[1]); w.y = cvt_pk_bf16(v[2], v[3]); w.z = cvt_pk_bf16(v[4], v[5]); w.w = cvt_pk_bf16(v[6], v[7]);
;                         *(u32x4*)(rowp + bj * HALF) = w; } }
	v_exp_f32_e32 v153, v153
	v_exp_f32_e32 v154, v154
	v_exp_f32_e32 v155, v155
	v_exp_f32_e32 v156, v156
	v_exp_f32_e32 v157, v157
	v_exp_f32_e32 v158, v158
	v_exp_f32_e32 v159, v159
	s_nop 0
	v_pk_add_f32 v[152:153], v[152:153], s[64:65]
	v_pk_add_f32 v[154:155], v[154:155], s[64:65]
	v_pk_add_f32 v[156:157], v[156:157], s[64:65]
	v_pk_add_f32 v[158:159], v[158:159], s[64:65]
	v_rcp_f32_e32 v152, v152
	v_rcp_f32_e32 v153, v153
	v_rcp_f32_e32 v154, v154
	v_rcp_f32_e32 v155, v155
	v_rcp_f32_e32 v156, v156
	v_rcp_f32_e32 v157, v157
	v_rcp_f32_e32 v158, v158
	v_rcp_f32_e32 v159, v159
	s_nop 0
	v_pk_mul_f32 v[152:153], v[84:85], v[152:153]
	v_pk_mul_f32 v[154:155], v[86:87], v[154:155]
	v_pk_mul_f32 v[156:157], v[80:81], v[156:157]
	v_pk_mul_f32 v[158:159], v[82:83], v[158:159]
	v_cvt_pk_bf16_f32 v180, v152, v153
	v_cvt_pk_bf16_f32 v181, v154, v155
	v_cvt_pk_bf16_f32 v182, v156, v157
	v_cvt_pk_bf16_f32 v183, v158, v159
	global_store_dwordx4 v150, v[180:183], s[24:25] offset:256
	s_add_u32 s24, s24, 0x8000
	s_addc_u32 s25, s25, 0
	v_pk_mul_f32 v[152:153], v[76:77], v[76:77]
	v_pk_mul_f32 v[154:155], v[78:79], v[78:79]
	v_pk_mul_f32 v[156:157], v[72:73], v[72:73]
	v_pk_mul_f32 v[158:159], v[74:75], v[74:75]
	v_fmaak_f32 v152, v151, v152, 0xc0135761
	v_fmaak_f32 v153, v151, v153, 0xc0135761
	v_fmaak_f32 v154, v151, v154, 0xc0135761
	v_fmaak_f32 v155, v151, v155, 0xc0135761
	v_fmaak_f32 v156, v151, v156, 0xc0135761
	v_fmaak_f32 v157, v151, v157, 0xc0135761
	v_fmaak_f32 v158, v151, v158, 0xc0135761
	v_fmaak_f32 v159, v151, v159, 0xc0135761
	v_pk_mul_f32 v[152:153], v[76:77], v[152:153]
	v_pk_mul_f32 v[154:155], v[78:79], v[154:155]
	v_pk_mul_f32 v[156:157], v[72:73], v[156:157]
	v_pk_mul_f32 v[158:159], v[74:75], v[158:159]
	v_exp_f32_e32 v152, v152
	v_exp_f32_e32 v153, v153
	v_exp_f32_e32 v154, v154
	v_exp_f32_e32 v155, v155
	v_exp_f32_e32 v156, v156
	v_exp_f32_e32 v157, v157
	v_exp_f32_e32 v158, v158
	v_exp_f32_e32 v159, v159
	s_nop 0
	v_pk_add_f32 v[152:153], v[152:153], s[64:65]
	v_pk_add_f32 v[154:155], v[154:155], s[64:65]
	v_pk_add_f32 v[156:157], v[156:157], s[64:65]
	v_pk_add_f32 v[158:159], v[158:159], s[64:65]
	v_rcp_f32_e32 v152, v152
	v_rcp_f32_e32 v153, v153
	v_rcp_f32_e32 v154, v154
	v_rcp_f32_e32 v155, v155
	v_rcp_f32_e32 v156, v156
	v_rcp_f32_e32 v157, v157
	v_rcp_f32_e32 v158, v158
	v_rcp_f32_e32 v159, v159
	s_nop 0
	v_pk_mul_f32 v[152:153], v[76:77], v[152:153]
	v_pk_mul_f32 v[154:155], v[78:79], v[154:155]
	v_pk_mul_f32 v[156:157], v[72:73], v[156:157]
	v_pk_mul_f32 v[158:159], v[74:75], v[158:159]
	v_cvt_pk_bf16_f32 v176, v152, v153
	v_cvt_pk_bf16_f32 v177, v154, v155
	v_cvt_pk_bf16_f32 v178, v156, v157
	v_cvt_pk_bf16_f32 v179, v158, v159
	global_store_dwordx4 v150, v[176:179], s[24:25]
	v_pk_mul_f32 v[152:153], v[68:69], v[68:69]
	v_pk_mul_f32 v[154:155], v[70:71], v[70:71]
	v_pk_mul_f32 v[156:157], v[64:65], v[64:65]
	v_pk_mul_f32 v[158:159], v[66:67], v[66:67]
	v_fmaak_f32 v152, v151, v152, 0xc0135761
	v_fmaak_f32 v153, v151, v153, 0xc0135761
	v_fmaak_f32 v154, v151, v154, 0xc0135761
	v_fmaak_f32 v155, v151, v155, 0xc0135761
	v_fmaak_f32 v156, v151, v156, 0xc0135761
	v_fmaak_f32 v157, v151, v157, 0xc0135761
	v_fmaak_f32 v158, v151, v158, 0xc0135761
	v_fmaak_f32 v159, v151, v159, 0xc0135761
	v_pk_mul_f32 v[152:153], v[68:69], v[152:153]
	v_pk_mul_f32 v[154:155], v[70:71], v[154:155]
	v_pk_mul_f32 v[156:157], v[64:65], v[156:157]
	v_pk_mul_f32 v[158:159], v[66:67], v[158:159]
	v_exp_f32_e32 v152, v152
	v_exp_f32_e32 v153, v153
	v_exp_f32_e32 v154, v154
	v_exp_f32_e32 v155, v155
	v_exp_f32_e32 v156, v156
	v_exp_f32_e32 v157, v157
	v_exp_f32_e32 v158, v158
	v_exp_f32_e32 v159, v159
	s_nop 0
	v_pk_add_f32 v[152:153], v[152:153], s[64:65]
	v_pk_add_f32 v[154:155], v[154:155], s[64:65]
	v_pk_add_f32 v[156:157], v[156:157], s[64:65]
	v_pk_add_f32 v[158:159], v[158:159], s[64:65]
	v_rcp_f32_e32 v152, v152
	v_rcp_f32_e32 v153, v153
	v_rcp_f32_e32 v154, v154
	v_rcp_f32_e32 v155, v155
	v_rcp_f32_e32 v156, v156
	v_rcp_f32_e32 v157, v157
	v_rcp_f32_e32 v158, v158
	v_rcp_f32_e32 v159, v159
	s_nop 0
	v_pk_mul_f32 v[152:153], v[68:69], v[152:153]
	v_pk_mul_f32 v[154:155], v[70:71], v[154:155]
	v_pk_mul_f32 v[156:157], v[64:65], v[156:157]
	v_pk_mul_f32 v[158:159], v[66:67], v[158:159]
	v_cvt_pk_bf16_f32 v180, v152, v153
	v_cvt_pk_bf16_f32 v181, v154, v155
	v_cvt_pk_bf16_f32 v182, v156, v157
	v_cvt_pk_bf16_f32 v183, v158, v159
	global_store_dwordx4 v150, v[180:183], s[24:25] offset:256
	s_add_u32 s24, s24, 0x28000
	s_addc_u32 s25, s25, 0
	v_pk_mul_f32 v[152:153], v[60:61], v[60:61]
	v_pk_mul_f32 v[154:155], v[62:63], v[62:63]
	v_pk_mul_f32 v[156:157], v[56:57], v[56:57]
	v_pk_mul_f32 v[158:159], v[58:59], v[58:59]
	v_fmaak_f32 v152, v151, v152, 0xc0135761
	v_fmaak_f32 v153, v151, v153, 0xc0135761
	v_fmaak_f32 v154, v151, v154, 0xc0135761
	v_fmaak_f32 v155, v151, v155, 0xc0135761
	v_fmaak_f32 v156, v151, v156, 0xc0135761
	v_fmaak_f32 v157, v151, v157, 0xc0135761
	v_fmaak_f32 v158, v151, v158, 0xc0135761
	v_fmaak_f32 v159, v151, v159, 0xc0135761
	v_pk_mul_f32 v[152:153], v[60:61], v[152:153]
	v_pk_mul_f32 v[154:155], v[62:63], v[154:155]
	v_pk_mul_f32 v[156:157], v[56:57], v[156:157]
	v_pk_mul_f32 v[158:159], v[58:59], v[158:159]
	v_exp_f32_e32 v152, v152
	v_exp_f32_e32 v153, v153
	v_exp_f32_e32 v154, v154
	v_exp_f32_e32 v155, v155
	v_exp_f32_e32 v156, v156
	v_exp_f32_e32 v157, v157
	v_exp_f32_e32 v158, v158
	v_exp_f32_e32 v159, v159
	s_nop 0
	v_pk_add_f32 v[152:153], v[152:153], s[64:65]
	v_pk_add_f32 v[154:155], v[154:155], s[64:65]
	v_pk_add_f32 v[156:157], v[156:157], s[64:65]
	v_pk_add_f32 v[158:159], v[158:159], s[64:65]
; __device__ __forceinline__ unsigned cvt_pk_bf16(float lo, float hi) { unsigned r; asm volatile("v_cvt_pk_bf16_f32 %0, %1, %2" : "=v"(r) : "v"(lo), "v"(hi)); return r; }
; __device__ __forceinline__ float sigmoid_f(float x) { return __builtin_amdgcn_rcpf(1.0f + __builtin_amdgcn_exp2f(-1.4426950409f * x)); }
;     __device__ __forceinline__ void operator()(f32x4 (&acc)[2][2][4][2], const Unit& u, int wr, int wc, int fr, int fq) const {
;     ...
;                 for (int m = 0; m < 4; ++m) { bf16_t* rowp = O + (size_t)(row0 + ai * HALF + m * 16) * LDP + col0;
; #pragma unroll
;                     for (int bj = 0; bj < 2; ++bj) {
;                         float v[8];
; #pragma unroll
;                         for (int j = 0; j < 4; ++j) { v[j] = acc[ai][bj][m][0][j]; v[4 + j] = acc[ai][bj][m][1][j]; }
;                         if (mode != 0) {
; #pragma unroll
;                             for (int j = 0; j < 8; ++j) {
;                                 const float x = v[j];
;                                 const float a = (mode == 1) ? 1.5957691216f * (x + 0.044715f * x * x * x) : x;
;                                 const float sg = sigmoid_f(a);
;                                 v[j] = (mode == 3) ? sg : x * sg;
;                             }
;                         }
;                         u32x4 w; w.x = cvt_pk_bf16(v[0], v[1]); w.y = cvt_pk_bf16(v[2], v[3]); w.z = cvt_pk_bf16(v[4], v[5]); w.w = cvt_pk_bf16(v[6], v[7]);
;                         *(u32x4*)(rowp + bj * HALF) = w; } }
	v_rcp_f32_e32 v152, v152
	v_rcp_f32_e32 v153, v153
	v_rcp_f32_e32 v154, v154
	v_rcp_f32_e32 v155, v155
	v_rcp_f32_e32 v156, v156
	v_rcp_f32_e32 v157, v157
	v_rcp_f32_e32 v158, v158
	v_rcp_f32_e32 v159, v159
	s_nop 0
	v_pk_mul_f32 v[152:153], v[60:61], v[152:153]
	v_pk_mul_f32 v[154:155], v[62:63], v[154:155]
	v_pk_mul_f32 v[156:157], v[56:57], v[156:157]
	v_pk_mul_f32 v[158:159], v[58:59], v[158:159]
	v_cvt_pk_bf16_f32 v176, v152, v153
	v_cvt_pk_bf16_f32 v177, v154, v155
	v_cvt_pk_bf16_f32 v178, v156, v157
	v_cvt_pk_bf16_f32 v179, v158, v159
	global_store_dwordx4 v150, v[176:179], s[24:25]
	v_pk_mul_f32 v[152:153], v[52:53], v[52:53]
	v_pk_mul_f32 v[154:155], v[54:55], v[54:55]
	v_pk_mul_f32 v[156:157], v[48:49], v[48:49]
	v_pk_mul_f32 v[158:159], v[50:51], v[50:51]
	v_fmaak_f32 v152, v151, v152, 0xc0135761
	v_fmaak_f32 v153, v151, v153, 0xc0135761
	v_fmaak_f32 v154, v151, v154, 0xc0135761
	v_fmaak_f32 v155, v151, v155, 0xc0135761
	v_fmaak_f32 v156, v151, v156, 0xc0135761
	v_fmaak_f32 v157, v151, v157, 0xc0135761
	v_fmaak_f32 v158, v151, v158, 0xc0135761
	v_fmaak_f32 v159, v151, v159, 0xc0135761
	v_pk_mul_f32 v[152:153], v[52:53], v[152:153]
	v_pk_mul_f32 v[154:155], v[54:55], v[154:155]
	v_pk_mul_f32 v[156:157], v[48:49], v[156:157]
	v_pk_mul_f32 v[158:159], v[50:51], v[158:159]
	v_exp_f32_e32 v152, v152
	v_exp_f32_e32 v153, v153
	v_exp_f32_e32 v154, v154
	v_exp_f32_e32 v155, v155
	v_exp_f32_e32 v156, v156
	v_exp_f32_e32 v157, v157
	v_exp_f32_e32 v158, v158
	v_exp_f32_e32 v159, v159
	s_nop 0
	v_pk_add_f32 v[152:153], v[152:153], s[64:65]
	v_pk_add_f32 v[154:155], v[154:155], s[64:65]
	v_pk_add_f32 v[156:157], v[156:157], s[64:65]
	v_pk_add_f32 v[158:159], v[158:159], s[64:65]
	v_rcp_f32_e32 v152, v152
	v_rcp_f32_e32 v153, v153
	v_rcp_f32_e32 v154, v154
	v_rcp_f32_e32 v155, v155
	v_rcp_f32_e32 v156, v156
	v_rcp_f32_e32 v157, v157
	v_rcp_f32_e32 v158, v158
	v_rcp_f32_e32 v159, v159
	s_nop 0
	v_pk_mul_f32 v[152:153], v[52:53], v[152:153]
	v_pk_mul_f32 v[154:155], v[54:55], v[154:155]
	v_pk_mul_f32 v[156:157], v[48:49], v[156:157]
	v_pk_mul_f32 v[158:159], v[50:51], v[158:159]
	v_cvt_pk_bf16_f32 v180, v152, v153
	v_cvt_pk_bf16_f32 v181, v154, v155
	v_cvt_pk_bf16_f32 v182, v156, v157
	v_cvt_pk_bf16_f32 v183, v158, v159
	global_store_dwordx4 v150, v[180:183], s[24:25] offset:256
	s_add_u32 s24, s24, 0x8000
	s_addc_u32 s25, s25, 0
	v_pk_mul_f32 v[152:153], v[44:45], v[44:45]
	v_pk_mul_f32 v[154:155], v[46:47], v[46:47]
	v_pk_mul_f32 v[156:157], v[40:41], v[40:41]
	v_pk_mul_f32 v[158:159], v[42:43], v[42:43]
	v_fmaak_f32 v152, v151, v152, 0xc0135761
	v_fmaak_f32 v153, v151, v153, 0xc0135761
	v_fmaak_f32 v154, v151, v154, 0xc0135761
	v_fmaak_f32 v155, v151, v155, 0xc0135761
	v_fmaak_f32 v156, v151, v156, 0xc0135761
	v_fmaak_f32 v157, v151, v157, 0xc0135761
	v_fmaak_f32 v158, v151, v158, 0xc0135761
	v_fmaak_f32 v159, v151, v159, 0xc0135761
	v_pk_mul_f32 v[152:153], v[44:45], v[152:153]
	v_pk_mul_f32 v[154:155], v[46:47], v[154:155]
	v_pk_mul_f32 v[156:157], v[40:41], v[156:157]
	v_pk_mul_f32 v[158:159], v[42:43], v[158:159]
	v_exp_f32_e32 v152, v152
	v_exp_f32_e32 v153, v153
	v_exp_f32_e32 v154, v154
	v_exp_f32_e32 v155, v155
	v_exp_f32_e32 v156, v156
	v_exp_f32_e32 v157, v157
	v_exp_f32_e32 v158, v158
	v_exp_f32_e32 v159, v159
	s_nop 0
	v_pk_add_f32 v[152:153], v[152:153], s[64:65]
	v_pk_add_f32 v[154:155], v[154:155], s[64:65]
	v_pk_add_f32 v[156:157], v[156:157], s[64:65]
	v_pk_add_f32 v[158:159], v[158:159], s[64:65]
	v_rcp_f32_e32 v152, v152
	v_rcp_f32_e32 v153, v153
	v_rcp_f32_e32 v154, v154
	v_rcp_f32_e32 v155, v155
	v_rcp_f32_e32 v156, v156
	v_rcp_f32_e32 v157, v157
	v_rcp_f32_e32 v158, v158
	v_rcp_f32_e32 v159, v159
	s_nop 0
	v_pk_mul_f32 v[152:153], v[44:45], v[152:153]
	v_pk_mul_f32 v[154:155], v[46:47], v[154:155]
	v_pk_mul_f32 v[156:157], v[40:41], v[156:157]
	v_pk_mul_f32 v[158:159], v[42:43], v[158:159]
	v_cvt_pk_bf16_f32 v176, v152, v153
	v_cvt_pk_bf16_f32 v177, v154, v155
	v_cvt_pk_bf16_f32 v178, v156, v157
	v_cvt_pk_bf16_f32 v179, v158, v159
	global_store_dwordx4 v150, v[176:179], s[24:25]
	v_pk_mul_f32 v[152:153], v[36:37], v[36:37]
	v_pk_mul_f32 v[154:155], v[38:39], v[38:39]
	v_pk_mul_f32 v[156:157], v[32:33], v[32:33]
	v_pk_mul_f32 v[158:159], v[34:35], v[34:35]
	v_fmaak_f32 v152, v151, v152, 0xc0135761
	v_fmaak_f32 v153, v151, v153, 0xc0135761
	v_fmaak_f32 v154, v151, v154, 0xc0135761
	v_fmaak_f32 v155, v151, v155, 0xc0135761
	v_fmaak_f32 v156, v151, v156, 0xc0135761
	v_fmaak_f32 v157, v151, v157, 0xc0135761
	v_fmaak_f32 v158, v151, v158, 0xc0135761
	v_fmaak_f32 v159, v151, v159, 0xc0135761
	v_pk_mul_f32 v[152:153], v[36:37], v[152:153]
	v_pk_mul_f32 v[154:155], v[38:39], v[154:155]
	v_pk_mul_f32 v[156:157], v[32:33], v[156:157]
	v_pk_mul_f32 v[158:159], v[34:35], v[158:159]
	v_exp_f32_e32 v152, v152
	v_exp_f32_e32 v153, v153
	v_exp_f32_e32 v154, v154
	v_exp_f32_e32 v155, v155
	v_exp_f32_e32 v156, v156
	v_exp_f32_e32 v157, v157
	v_exp_f32_e32 v158, v158
	v_exp_f32_e32 v159, v159
	s_nop 0
	v_pk_add_f32 v[152:153], v[152:153], s[64:65]
	v_pk_add_f32 v[154:155], v[154:155], s[64:65]
	v_pk_add_f32 v[156:157], v[156:157], s[64:65]
	v_pk_add_f32 v[158:159], v[158:159], s[64:65]
	v_rcp_f32_e32 v152, v152
	v_rcp_f32_e32 v153, v153
	v_rcp_f32_e32 v154, v154
	v_rcp_f32_e32 v155, v155
	v_rcp_f32_e32 v156, v156
	v_rcp_f32_e32 v157, v157
	v_rcp_f32_e32 v158, v158
	v_rcp_f32_e32 v159, v159
	s_nop 0
	v_pk_mul_f32 v[152:153], v[36:37], v[152:153]
	v_pk_mul_f32 v[154:155], v[38:39], v[154:155]
	v_pk_mul_f32 v[156:157], v[32:33], v[156:157]
	v_pk_mul_f32 v[158:159], v[34:35], v[158:159]
	v_cvt_pk_bf16_f32 v180, v152, v153
; __device__ __forceinline__ unsigned cvt_pk_bf16(float lo, float hi) { unsigned r; asm volatile("v_cvt_pk_bf16_f32 %0, %1, %2" : "=v"(r) : "v"(lo), "v"(hi)); return r; }
; __device__ __forceinline__ float sigmoid_f(float x) { return __builtin_amdgcn_rcpf(1.0f + __builtin_amdgcn_exp2f(-1.4426950409f * x)); }
;     __device__ __forceinline__ void operator()(f32x4 (&acc)[2][2][4][2], const Unit& u, int wr, int wc, int fr, int fq) const {
;     ...
;                 for (int m = 0; m < 4; ++m) { bf16_t* rowp = O + (size_t)(row0 + ai * HALF + m * 16) * LDP + col0;
; #pragma unroll
;                     for (int bj = 0; bj < 2; ++bj) {
;                         float v[8];
; #pragma unroll
;                         for (int j = 0; j < 4; ++j) { v[j] = acc[ai][bj][m][0][j]; v[4 + j] = acc[ai][bj][m][1][j]; }
;                         if (mode != 0) {
; #pragma unroll
;                             for (int j = 0; j < 8; ++j) {
;                                 const float x = v[j];
;                                 const float a = (mode == 1) ? 1.5957691216f * (x + 0.044715f * x * x * x) : x;
;                                 const float sg = sigmoid_f(a);
;                                 v[j] = (mode == 3) ? sg : x * sg;
;                             }
;                         }
;                         u32x4 w; w.x = cvt_pk_bf16(v[0], v[1]); w.y = cvt_pk_bf16(v[2], v[3]); w.z = cvt_pk_bf16(v[4], v[5]); w.w = cvt_pk_bf16(v[6], v[7]);
;                         *(u32x4*)(rowp + bj * HALF) = w; } }
	v_cvt_pk_bf16_f32 v181, v154, v155
	v_cvt_pk_bf16_f32 v182, v156, v157
	v_cvt_pk_bf16_f32 v183, v158, v159
	global_store_dwordx4 v150, v[180:183], s[24:25] offset:256
	s_add_u32 s24, s24, 0x8000
	s_addc_u32 s25, s25, 0
	v_pk_mul_f32 v[152:153], v[28:29], v[28:29]
	v_pk_mul_f32 v[154:155], v[30:31], v[30:31]
	v_pk_mul_f32 v[156:157], v[24:25], v[24:25]
	v_pk_mul_f32 v[158:159], v[26:27], v[26:27]
	v_fmaak_f32 v152, v151, v152, 0xc0135761
	v_fmaak_f32 v153, v151, v153, 0xc0135761
	v_fmaak_f32 v154, v151, v154, 0xc0135761
	v_fmaak_f32 v155, v151, v155, 0xc0135761
	v_fmaak_f32 v156, v151, v156, 0xc0135761
	v_fmaak_f32 v157, v151, v157, 0xc0135761
	v_fmaak_f32 v158, v151, v158, 0xc0135761
	v_fmaak_f32 v159, v151, v159, 0xc0135761
	v_pk_mul_f32 v[152:153], v[28:29], v[152:153]
	v_pk_mul_f32 v[154:155], v[30:31], v[154:155]
	v_pk_mul_f32 v[156:157], v[24:25], v[156:157]
	v_pk_mul_f32 v[158:159], v[26:27], v[158:159]
	v_exp_f32_e32 v152, v152
	v_exp_f32_e32 v153, v153
	v_exp_f32_e32 v154, v154
	v_exp_f32_e32 v155, v155
	v_exp_f32_e32 v156, v156
	v_exp_f32_e32 v157, v157
	v_exp_f32_e32 v158, v158
	v_exp_f32_e32 v159, v159
	s_nop 0
	v_pk_add_f32 v[152:153], v[152:153], s[64:65]
	v_pk_add_f32 v[154:155], v[154:155], s[64:65]
	v_pk_add_f32 v[156:157], v[156:157], s[64:65]
	v_pk_add_f32 v[158:159], v[158:159], s[64:65]
	v_rcp_f32_e32 v152, v152
	v_rcp_f32_e32 v153, v153
	v_rcp_f32_e32 v154, v154
	v_rcp_f32_e32 v155, v155
	v_rcp_f32_e32 v156, v156
	v_rcp_f32_e32 v157, v157
	v_rcp_f32_e32 v158, v158
	v_rcp_f32_e32 v159, v159
	s_nop 0
	v_pk_mul_f32 v[152:153], v[28:29], v[152:153]
	v_pk_mul_f32 v[154:155], v[30:31], v[154:155]
	v_pk_mul_f32 v[156:157], v[24:25], v[156:157]
	v_pk_mul_f32 v[158:159], v[26:27], v[158:159]
	v_cvt_pk_bf16_f32 v176, v152, v153
	v_cvt_pk_bf16_f32 v177, v154, v155
	v_cvt_pk_bf16_f32 v178, v156, v157
	v_cvt_pk_bf16_f32 v179, v158, v159
	global_store_dwordx4 v150, v[176:179], s[24:25]
	v_pk_mul_f32 v[152:153], v[20:21], v[20:21]
	v_pk_mul_f32 v[154:155], v[22:23], v[22:23]
	v_pk_mul_f32 v[156:157], v[16:17], v[16:17]
	v_pk_mul_f32 v[158:159], v[18:19], v[18:19]
	v_fmaak_f32 v152, v151, v152, 0xc0135761
	v_fmaak_f32 v153, v151, v153, 0xc0135761
	v_fmaak_f32 v154, v151, v154, 0xc0135761
	v_fmaak_f32 v155, v151, v155, 0xc0135761
	v_fmaak_f32 v156, v151, v156, 0xc0135761
	v_fmaak_f32 v157, v151, v157, 0xc0135761
	v_fmaak_f32 v158, v151, v158, 0xc0135761
	v_fmaak_f32 v159, v151, v159, 0xc0135761
	v_pk_mul_f32 v[152:153], v[20:21], v[152:153]
	v_pk_mul_f32 v[154:155], v[22:23], v[154:155]
	v_pk_mul_f32 v[156:157], v[16:17], v[156:157]
	v_pk_mul_f32 v[158:159], v[18:19], v[158:159]
	v_exp_f32_e32 v152, v152
	v_exp_f32_e32 v153, v153
	v_exp_f32_e32 v154, v154
	v_exp_f32_e32 v155, v155
	v_exp_f32_e32 v156, v156
	v_exp_f32_e32 v157, v157
	v_exp_f32_e32 v158, v158
	v_exp_f32_e32 v159, v159
	s_nop 0
	v_pk_add_f32 v[152:153], v[152:153], s[64:65]
	v_pk_add_f32 v[154:155], v[154:155], s[64:65]
	v_pk_add_f32 v[156:157], v[156:157], s[64:65]
	v_pk_add_f32 v[158:159], v[158:159], s[64:65]
	v_rcp_f32_e32 v152, v152
	v_rcp_f32_e32 v153, v153
	v_rcp_f32_e32 v154, v154
	v_rcp_f32_e32 v155, v155
	v_rcp_f32_e32 v156, v156
	v_rcp_f32_e32 v157, v157
	v_rcp_f32_e32 v158, v158
	v_rcp_f32_e32 v159, v159
	s_nop 0
	v_pk_mul_f32 v[152:153], v[20:21], v[152:153]
	v_pk_mul_f32 v[154:155], v[22:23], v[154:155]
	v_pk_mul_f32 v[156:157], v[16:17], v[156:157]
	v_pk_mul_f32 v[158:159], v[18:19], v[158:159]
	v_cvt_pk_bf16_f32 v180, v152, v153
	v_cvt_pk_bf16_f32 v181, v154, v155
	v_cvt_pk_bf16_f32 v182, v156, v157
; __device__ __forceinline__ unsigned cvt_pk_bf16(float lo, float hi) { unsigned r; asm volatile("v_cvt_pk_bf16_f32 %0, %1, %2" : "=v"(r) : "v"(lo), "v"(hi)); return r; }
; __device__ __forceinline__ float sigmoid_f(float x) { return __builtin_amdgcn_rcpf(1.0f + __builtin_amdgcn_exp2f(-1.4426950409f * x)); }
;     __device__ __forceinline__ void operator()(f32x4 (&acc)[2][2][4][2], const Unit& u, int wr, int wc, int fr, int fq) const {
;     ...
;                 for (int m = 0; m < 4; ++m) { bf16_t* rowp = O + (size_t)(row0 + ai * HALF + m * 16) * LDP + col0;
; #pragma unroll
;                     for (int bj = 0; bj < 2; ++bj) {
;                         float v[8];
; #pragma unroll
;                         for (int j = 0; j < 4; ++j) { v[j] = acc[ai][bj][m][0][j]; v[4 + j] = acc[ai][bj][m][1][j]; }
;                         if (mode != 0) {
; #pragma unroll
;                             for (int j = 0; j < 8; ++j) {
;                                 const float x = v[j];
;                                 const float a = (mode == 1) ? 1.5957691216f * (x + 0.044715f * x * x * x) : x;
;                                 const float sg = sigmoid_f(a);
;                                 v[j] = (mode == 3) ? sg : x * sg;
;                             }
;                         }
;                         u32x4 w; w.x = cvt_pk_bf16(v[0], v[1]); w.y = cvt_pk_bf16(v[2], v[3]); w.z = cvt_pk_bf16(v[4], v[5]); w.w = cvt_pk_bf16(v[6], v[7]);
;                         *(u32x4*)(rowp + bj * HALF) = w; } }
	v_cvt_pk_bf16_f32 v183, v158, v159
	global_store_dwordx4 v150, v[180:183], s[24:25] offset:256
	s_add_u32 s24, s24, 0x8000
	s_addc_u32 s25, s25, 0
	v_pk_mul_f32 v[152:153], v[12:13], v[12:13]
	v_pk_mul_f32 v[154:155], v[14:15], v[14:15]
	v_pk_mul_f32 v[156:157], v[8:9], v[8:9]
	v_pk_mul_f32 v[158:159], v[10:11], v[10:11]
	v_fmaak_f32 v152, v151, v152, 0xc0135761
	v_fmaak_f32 v153, v151, v153, 0xc0135761
	v_fmaak_f32 v154, v151, v154, 0xc0135761
	v_fmaak_f32 v155, v151, v155, 0xc0135761
	v_fmaak_f32 v156, v151, v156, 0xc0135761
	v_fmaak_f32 v157, v151, v157, 0xc0135761
	v_fmaak_f32 v158, v151, v158, 0xc0135761
	v_fmaak_f32 v159, v151, v159, 0xc0135761
	v_pk_mul_f32 v[152:153], v[12:13], v[152:153]
	v_pk_mul_f32 v[154:155], v[14:15], v[154:155]
	v_pk_mul_f32 v[156:157], v[8:9], v[156:157]
	v_pk_mul_f32 v[158:159], v[10:11], v[158:159]
	v_exp_f32_e32 v152, v152
	v_exp_f32_e32 v153, v153
	v_exp_f32_e32 v154, v154
	v_exp_f32_e32 v155, v155
	v_exp_f32_e32 v156, v156
	v_exp_f32_e32 v157, v157
	v_exp_f32_e32 v158, v158
	v_exp_f32_e32 v159, v159
	s_nop 0
	v_pk_add_f32 v[152:153], v[152:153], s[64:65]
	v_pk_add_f32 v[154:155], v[154:155], s[64:65]
	v_pk_add_f32 v[156:157], v[156:157], s[64:65]
	v_pk_add_f32 v[158:159], v[158:159], s[64:65]
	v_rcp_f32_e32 v152, v152
	v_rcp_f32_e32 v153, v153
	v_rcp_f32_e32 v154, v154
	v_rcp_f32_e32 v155, v155
	v_rcp_f32_e32 v156, v156
	v_rcp_f32_e32 v157, v157
	v_rcp_f32_e32 v158, v158
	v_rcp_f32_e32 v159, v159
	s_nop 0
	v_pk_mul_f32 v[152:153], v[12:13], v[152:153]
	v_pk_mul_f32 v[154:155], v[14:15], v[154:155]
	v_pk_mul_f32 v[156:157], v[8:9], v[156:157]
	v_pk_mul_f32 v[158:159], v[10:11], v[158:159]
	v_cvt_pk_bf16_f32 v176, v152, v153
	v_cvt_pk_bf16_f32 v177, v154, v155
	v_cvt_pk_bf16_f32 v178, v156, v157
	v_cvt_pk_bf16_f32 v179, v158, v159
	global_store_dwordx4 v150, v[176:179], s[24:25]
	v_pk_mul_f32 v[152:153], v[4:5], v[4:5]
	v_pk_mul_f32 v[154:155], v[6:7], v[6:7]
	v_pk_mul_f32 v[156:157], v[0:1], v[0:1]
	v_pk_mul_f32 v[158:159], v[2:3], v[2:3]
	v_fmaak_f32 v152, v151, v152, 0xc0135761
	v_fmaak_f32 v153, v151, v153, 0xc0135761
	v_fmaak_f32 v154, v151, v154, 0xc0135761
	v_fmaak_f32 v155, v151, v155, 0xc0135761
	v_fmaak_f32 v156, v151, v156, 0xc0135761
	v_fmaak_f32 v157, v151, v157, 0xc0135761
	v_fmaak_f32 v158, v151, v158, 0xc0135761
	v_fmaak_f32 v159, v151, v159, 0xc0135761
	v_pk_mul_f32 v[152:153], v[4:5], v[152:153]
	v_pk_mul_f32 v[154:155], v[6:7], v[154:155]
	v_pk_mul_f32 v[156:157], v[0:1], v[156:157]
	v_pk_mul_f32 v[158:159], v[2:3], v[158:159]
	v_exp_f32_e32 v152, v152
	v_exp_f32_e32 v153, v153
	v_exp_f32_e32 v154, v154
	v_exp_f32_e32 v155, v155
	v_exp_f32_e32 v156, v156
	v_exp_f32_e32 v157, v157
	v_exp_f32_e32 v158, v158
	v_exp_f32_e32 v159, v159
	s_nop 0
	v_pk_add_f32 v[152:153], v[152:153], s[64:65]
	v_pk_add_f32 v[154:155], v[154:155], s[64:65]
	v_pk_add_f32 v[156:157], v[156:157], s[64:65]
	v_pk_add_f32 v[158:159], v[158:159], s[64:65]
	v_rcp_f32_e32 v152, v152
	v_rcp_f32_e32 v153, v153
	v_rcp_f32_e32 v154, v154
	v_rcp_f32_e32 v155, v155
	v_rcp_f32_e32 v156, v156
	v_rcp_f32_e32 v157, v157
	v_rcp_f32_e32 v158, v158
	v_rcp_f32_e32 v159, v159
	s_nop 0
	v_pk_mul_f32 v[152:153], v[4:5], v[152:153]
	v_pk_mul_f32 v[154:155], v[6:7], v[154:155]
	v_pk_mul_f32 v[156:157], v[0:1], v[156:157]
	v_pk_mul_f32 v[158:159], v[2:3], v[158:159]
	v_cvt_pk_bf16_f32 v180, v152, v153
	v_cvt_pk_bf16_f32 v181, v154, v155
	v_cvt_pk_bf16_f32 v182, v156, v157
	v_cvt_pk_bf16_f32 v183, v158, v159
	global_store_dwordx4 v150, v[180:183], s[24:25] offset:256
	s_branch .LBB0_298

;     __device__ __forceinline__ void operator()(f32x4 (&acc)[2][2][4][2], const Unit& u, int wr, int wc, int fr, int fq) const {
;     ...
;         if (mode == 7) {
;             const int row0q = u.pm * BM + wr * 64 + fr; const int ch = 64 * (pn - 32) + 16 * wc + 4 * fq;
; #pragma unroll
;             for (int ai = 0; ai < 2; ++ai)
; #pragma unroll
;                 for (int m = 0; m < 4; ++m) {
;                     bf16_t* rowp = O + (size_t)(row0q + ai * HALF + m * 16) * LDP + ch;
;                     float r0v[4], r1v[4], g2v[4], szv[4];
; #pragma unroll
;                     for (int j = 0; j < 4; ++j) {
;                         const float ea = fminf(__builtin_amdgcn_exp2f(-1.4426950409f * acc[ai][0][m][0][j]), 1e30f);
;                         const float eb = fminf(__builtin_amdgcn_exp2f(-1.4426950409f * acc[ai][0][m][1][j]), 1e30f);
;                         const float ec = fminf(__builtin_amdgcn_exp2f(-1.4426950409f * acc[ai][1][m][0][j]), 1e30f);
;                         const float xz = acc[ai][1][m][1][j];
;                         const float ia = __builtin_amdgcn_rcpf(1.0f + ea), ib = __builtin_amdgcn_rcpf(1.0f + eb), ic = __builtin_amdgcn_rcpf(1.0f + ec);
;                         r0v[j] = (1.0f + eb) * ia; r1v[j] = (1.0f + ec) * ib; g2v[j] = ic; szv[j] = xz * sigmoid_f(xz);
;                     }
;                     u32x2 wr0, wr1, wg2, wsz;
;                     wr0.x = cvt_pk_bf16(r0v[0], r0v[1]); wr0.y = cvt_pk_bf16(r0v[2], r0v[3]);
;                     wr1.x = cvt_pk_bf16(r1v[0], r1v[1]); wr1.y = cvt_pk_bf16(r1v[2], r1v[3]);
;                     wg2.x = cvt_pk_bf16(g2v[0], g2v[1]); wg2.y = cvt_pk_bf16(g2v[2], g2v[3]);
;                     wsz.x = cvt_pk_bf16(szv[0], szv[1]); wsz.y = cvt_pk_bf16(szv[2], szv[3]);
;                     const bool odd = (fq & 1) != 0;
;                     const u32x2 s0 = odd ? wr0 : wg2, s1 = odd ? wr1 : wsz;
;                     u32x2 q0, q1;
;                     q0.x = (unsigned)__shfl_xor((int)s0.x, 16); q0.y = (unsigned)__shfl_xor((int)s0.y, 16);
;                     q1.x = (unsigned)__shfl_xor((int)s1.x, 16); q1.y = (unsigned)__shfl_xor((int)s1.y, 16);
;                     u32x4 o0, o1;
;                     if (!odd) { o0 = (u32x4){wr0.x, wr0.y, q0.x, q0.y}; o1 = (u32x4){wr1.x, wr1.y, q1.x, q1.y}; }
.LBB0_424:
	v_mov_b32_e32 v184, 8
	v_cndmask_b32_e64 v184, v184, 0, s[38:39]
	v_lshlrev_b32_e32 v185, 11, v164
	v_add_u32_e32 v185, v185, v136
	v_sub_u32_e32 v185, v185, v184
	v_mov_b32_e32 v186, 0x20000000
	v_mov_b32_e32 v187, 0x14000000
	v_cndmask_b32_e64 v186, v186, v187, s[38:39]
	v_add_u32_e32 v150, v185, v186
	v_mov_b32_e32 v186, 0xc000000
	v_mov_b32_e32 v187, 0x1c000000
	v_cndmask_b32_e64 v186, v186, v187, s[38:39]
	v_add_u32_e32 v151, v185, v186
	s_lshl_b32 s14, s60, 19
	s_add_u32 s24, s70, s14
	s_addc_u32 s25, s71, 0
	s_lshl_b32 s14, s59, 7
	s_sub_u32 s14, s14, 0x1000
	s_add_u32 s24, s24, s14
	s_addc_u32 s25, s25, 0
	v_pk_mul_f32 v[124:125], v[124:125], s[62:63]
	v_pk_mul_f32 v[126:127], v[126:127], s[62:63]
	v_pk_mul_f32 v[120:121], v[120:121], s[62:63]
	v_pk_mul_f32 v[122:123], v[122:123], s[62:63]
	v_pk_mul_f32 v[116:117], v[116:117], s[62:63]
	v_pk_mul_f32 v[118:119], v[118:119], s[62:63]
	v_pk_mul_f32 v[160:161], v[112:113], s[62:63]
	v_pk_mul_f32 v[162:163], v[114:115], s[62:63]
	v_exp_f32_e32 v124, v124
	v_exp_f32_e32 v125, v125
	v_exp_f32_e32 v126, v126
	v_exp_f32_e32 v127, v127
	v_exp_f32_e32 v120, v120
	v_exp_f32_e32 v121, v121
	v_exp_f32_e32 v122, v122
	v_exp_f32_e32 v123, v123
	v_exp_f32_e32 v116, v116
	v_exp_f32_e32 v117, v117
	v_exp_f32_e32 v118, v118
	v_exp_f32_e32 v119, v119
	v_exp_f32_e32 v160, v160
	v_exp_f32_e32 v161, v161
	v_exp_f32_e32 v162, v162
	v_exp_f32_e32 v163, v163
	v_min_f32_e32 v124, 0x7149f2ca, v124
	v_min_f32_e32 v125, 0x7149f2ca, v125
	v_min_f32_e32 v126, 0x7149f2ca, v126
	v_min_f32_e32 v127, 0x7149f2ca, v127
	v_min_f32_e32 v120, 0x7149f2ca, v120
	v_min_f32_e32 v121, 0x7149f2ca, v121
	v_min_f32_e32 v122, 0x7149f2ca, v122
	v_min_f32_e32 v123, 0x7149f2ca, v123
	v_min_f32_e32 v116, 0x7149f2ca, v116
	v_min_f32_e32 v117, 0x7149f2ca, v117
	v_min_f32_e32 v118, 0x7149f2ca, v118
	v_min_f32_e32 v119, 0x7149f2ca, v119
	v_pk_add_f32 v[124:125], v[124:125], s[64:65]
	v_pk_add_f32 v[126:127], v[126:127], s[64:65]
	v_pk_add_f32 v[120:121], v[120:121], s[64:65]
	v_pk_add_f32 v[122:123], v[122:123], s[64:65]
	v_pk_add_f32 v[116:117], v[116:117], s[64:65]
	v_pk_add_f32 v[118:119], v[118:119], s[64:65]
	v_pk_add_f32 v[160:161], v[160:161], s[64:65]
	v_pk_add_f32 v[162:163], v[162:163], s[64:65]
	v_rcp_f32_e32 v152, v124
	v_rcp_f32_e32 v153, v125
	v_rcp_f32_e32 v154, v126
	v_rcp_f32_e32 v155, v127
	v_rcp_f32_e32 v156, v120
	v_rcp_f32_e32 v157, v121
	v_rcp_f32_e32 v158, v122
	v_rcp_f32_e32 v159, v123
	v_rcp_f32_e32 v160, v160
	v_rcp_f32_e32 v161, v161
	v_rcp_f32_e32 v162, v162
	v_rcp_f32_e32 v163, v163
	v_pk_mul_f32 v[152:153], v[120:121], v[152:153]
	v_pk_mul_f32 v[154:155], v[122:123], v[154:155]
	v_pk_mul_f32 v[156:157], v[116:117], v[156:157]
	v_pk_mul_f32 v[158:159], v[118:119], v[158:159]
	v_rcp_f32_e32 v116, v116
	v_rcp_f32_e32 v117, v117
	v_rcp_f32_e32 v118, v118
	v_rcp_f32_e32 v119, v119
	v_pk_mul_f32 v[160:161], v[112:113], v[160:161]
	v_pk_mul_f32 v[162:163], v[114:115], v[162:163]
	v_cvt_pk_bf16_f32 v168, v152, v153
	v_cvt_pk_bf16_f32 v169, v154, v155
	v_cvt_pk_bf16_f32 v172, v156, v157
	v_cvt_pk_bf16_f32 v173, v158, v159
	v_cvt_pk_bf16_f32 v174, v160, v161
	v_cvt_pk_bf16_f32 v175, v162, v163
	v_cvt_pk_bf16_f32 v170, v116, v117
	v_cvt_pk_bf16_f32 v171, v118, v119
	s_nop 1
	v_permlane16_swap_b32_e32 v172, v174
	v_permlane16_swap_b32_e32 v173, v175
	v_permlane16_swap_b32_e32 v168, v170
	v_permlane16_swap_b32_e32 v169, v171
	global_store_dwordx4 v151, v[172:175], s[24:25]
	global_store_dwordx4 v150, v[168:171], s[24:25]
	s_add_u32 s24, s24, 0x8000
	s_addc_u32 s25, s25, 0
	v_pk_mul_f32 v[108:109], v[108:109], s[62:63]
	v_pk_mul_f32 v[110:111], v[110:111], s[62:63]
	v_pk_mul_f32 v[104:105], v[104:105], s[62:63]
	v_pk_mul_f32 v[106:107], v[106:107], s[62:63]
	v_pk_mul_f32 v[100:101], v[100:101], s[62:63]
	v_pk_mul_f32 v[102:103], v[102:103], s[62:63]
	v_pk_mul_f32 v[160:161], v[96:97], s[62:63]
	v_pk_mul_f32 v[162:163], v[98:99], s[62:63]
	v_exp_f32_e32 v108, v108
	v_exp_f32_e32 v109, v109
	v_exp_f32_e32 v110, v110
	v_exp_f32_e32 v111, v111
	v_exp_f32_e32 v104, v104
	v_exp_f32_e32 v105, v105
	v_exp_f32_e32 v106, v106
	v_exp_f32_e32 v107, v107
	v_exp_f32_e32 v100, v100
	v_exp_f32_e32 v101, v101
	v_exp_f32_e32 v102, v102
	v_exp_f32_e32 v103, v103
	v_exp_f32_e32 v160, v160
	v_exp_f32_e32 v161, v161
	v_exp_f32_e32 v162, v162
	v_exp_f32_e32 v163, v163
	v_min_f32_e32 v108, 0x7149f2ca, v108
	v_min_f32_e32 v109, 0x7149f2ca, v109
	v_min_f32_e32 v110, 0x7149f2ca, v110
	v_min_f32_e32 v111, 0x7149f2ca, v111
	v_min_f32_e32 v104, 0x7149f2ca, v104
	v_min_f32_e32 v105, 0x7149f2ca, v105
	v_min_f32_e32 v106, 0x7149f2ca, v106
	v_min_f32_e32 v107, 0x7149f2ca, v107
	v_min_f32_e32 v100, 0x7149f2ca, v100
	v_min_f32_e32 v101, 0x7149f2ca, v101
	v_min_f32_e32 v102, 0x7149f2ca, v102
	v_min_f32_e32 v103, 0x7149f2ca, v103
	v_pk_add_f32 v[108:109], v[108:109], s[64:65]
	v_pk_add_f32 v[110:111], v[110:111], s[64:65]
	v_pk_add_f32 v[104:105], v[104:105], s[64:65]
	v_pk_add_f32 v[106:107], v[106:107], s[64:65]
	v_pk_add_f32 v[100:101], v[100:101], s[64:65]
	v_pk_add_f32 v[102:103], v[102:103], s[64:65]
	v_pk_add_f32 v[160:161], v[160:161], s[64:65]
	v_pk_add_f32 v[162:163], v[162:163], s[64:65]
	v_rcp_f32_e32 v152, v108
	v_rcp_f32_e32 v153, v109
	v_rcp_f32_e32 v154, v110
	v_rcp_f32_e32 v155, v111
	v_rcp_f32_e32 v156, v104
	v_rcp_f32_e32 v157, v105
	v_rcp_f32_e32 v158, v106
	v_rcp_f32_e32 v159, v107
	v_rcp_f32_e32 v160, v160
	v_rcp_f32_e32 v161, v161
	v_rcp_f32_e32 v162, v162
	v_rcp_f32_e32 v163, v163
	v_pk_mul_f32 v[152:153], v[104:105], v[152:153]
	v_pk_mul_f32 v[154:155], v[106:107], v[154:155]
	v_pk_mul_f32 v[156:157], v[100:101], v[156:157]
;     __device__ __forceinline__ void operator()(f32x4 (&acc)[2][2][4][2], const Unit& u, int wr, int wc, int fr, int fq) const {
;     ...
;         if (mode == 7) {
;             const int row0q = u.pm * BM + wr * 64 + fr; const int ch = 64 * (pn - 32) + 16 * wc + 4 * fq;
; #pragma unroll
;             for (int ai = 0; ai < 2; ++ai)
; #pragma unroll
;                 for (int m = 0; m < 4; ++m) {
;                     bf16_t* rowp = O + (size_t)(row0q + ai * HALF + m * 16) * LDP + ch;
;                     float r0v[4], r1v[4], g2v[4], szv[4];
; #pragma unroll
;                     for (int j = 0; j < 4; ++j) {
;                         const float ea = fminf(__builtin_amdgcn_exp2f(-1.4426950409f * acc[ai][0][m][0][j]), 1e30f);
;                         const float eb = fminf(__builtin_amdgcn_exp2f(-1.4426950409f * acc[ai][0][m][1][j]), 1e30f);
;                         const float ec = fminf(__builtin_amdgcn_exp2f(-1.4426950409f * acc[ai][1][m][0][j]), 1e30f);
;                         const float xz = acc[ai][1][m][1][j];
;                         const float ia = __builtin_amdgcn_rcpf(1.0f + ea), ib = __builtin_amdgcn_rcpf(1.0f + eb), ic = __builtin_amdgcn_rcpf(1.0f + ec);
;                         r0v[j] = (1.0f + eb) * ia; r1v[j] = (1.0f + ec) * ib; g2v[j] = ic; szv[j] = xz * sigmoid_f(xz);
;                     }
;                     u32x2 wr0, wr1, wg2, wsz;
;                     wr0.x = cvt_pk_bf16(r0v[0], r0v[1]); wr0.y = cvt_pk_bf16(r0v[2], r0v[3]);
;                     wr1.x = cvt_pk_bf16(r1v[0], r1v[1]); wr1.y = cvt_pk_bf16(r1v[2], r1v[3]);
;                     wg2.x = cvt_pk_bf16(g2v[0], g2v[1]); wg2.y = cvt_pk_bf16(g2v[2], g2v[3]);
;                     wsz.x = cvt_pk_bf16(szv[0], szv[1]); wsz.y = cvt_pk_bf16(szv[2], szv[3]);
;                     const bool odd = (fq & 1) != 0;
;                     const u32x2 s0 = odd ? wr0 : wg2, s1 = odd ? wr1 : wsz;
;                     u32x2 q0, q1;
;                     q0.x = (unsigned)__shfl_xor((int)s0.x, 16); q0.y = (unsigned)__shfl_xor((int)s0.y, 16);
;                     q1.x = (unsigned)__shfl_xor((int)s1.x, 16); q1.y = (unsigned)__shfl_xor((int)s1.y, 16);
;                     u32x4 o0, o1;
;                     if (!odd) { o0 = (u32x4){wr0.x, wr0.y, q0.x, q0.y}; o1 = (u32x4){wr1.x, wr1.y, q1.x, q1.y}; }
	v_pk_mul_f32 v[158:159], v[102:103], v[158:159]
	v_rcp_f32_e32 v100, v100
	v_rcp_f32_e32 v101, v101
	v_rcp_f32_e32 v102, v102
	v_rcp_f32_e32 v103, v103
	v_pk_mul_f32 v[160:161], v[96:97], v[160:161]
	v_pk_mul_f32 v[162:163], v[98:99], v[162:163]
	v_cvt_pk_bf16_f32 v176, v152, v153
	v_cvt_pk_bf16_f32 v177, v154, v155
	v_cvt_pk_bf16_f32 v180, v156, v157
	v_cvt_pk_bf16_f32 v181, v158, v159
	v_cvt_pk_bf16_f32 v182, v160, v161
	v_cvt_pk_bf16_f32 v183, v162, v163
	v_cvt_pk_bf16_f32 v178, v100, v101
	v_cvt_pk_bf16_f32 v179, v102, v103
	s_nop 1
	v_permlane16_swap_b32_e32 v180, v182
	v_permlane16_swap_b32_e32 v181, v183
	v_permlane16_swap_b32_e32 v176, v178
	v_permlane16_swap_b32_e32 v177, v179
	global_store_dwordx4 v151, v[180:183], s[24:25]
	global_store_dwordx4 v150, v[176:179], s[24:25]
	s_add_u32 s24, s24, 0x8000
	s_addc_u32 s25, s25, 0
	v_pk_mul_f32 v[92:93], v[92:93], s[62:63]
	v_pk_mul_f32 v[94:95], v[94:95], s[62:63]
	v_pk_mul_f32 v[88:89], v[88:89], s[62:63]
	v_pk_mul_f32 v[90:91], v[90:91], s[62:63]
	v_pk_mul_f32 v[84:85], v[84:85], s[62:63]
	v_pk_mul_f32 v[86:87], v[86:87], s[62:63]
	v_pk_mul_f32 v[160:161], v[80:81], s[62:63]
	v_pk_mul_f32 v[162:163], v[82:83], s[62:63]
	v_exp_f32_e32 v92, v92
	v_exp_f32_e32 v93, v93
	v_exp_f32_e32 v94, v94
	v_exp_f32_e32 v95, v95
	v_exp_f32_e32 v88, v88
	v_exp_f32_e32 v89, v89
	v_exp_f32_e32 v90, v90
	v_exp_f32_e32 v91, v91
	v_exp_f32_e32 v84, v84
	v_exp_f32_e32 v85, v85
	v_exp_f32_e32 v86, v86
	v_exp_f32_e32 v87, v87
	v_exp_f32_e32 v160, v160
	v_exp_f32_e32 v161, v161
	v_exp_f32_e32 v162, v162
	v_exp_f32_e32 v163, v163
	v_min_f32_e32 v92, 0x7149f2ca, v92
	v_min_f32_e32 v93, 0x7149f2ca, v93
	v_min_f32_e32 v94, 0x7149f2ca, v94
	v_min_f32_e32 v95, 0x7149f2ca, v95
	v_min_f32_e32 v88, 0x7149f2ca, v88
	v_min_f32_e32 v89, 0x7149f2ca, v89
	v_min_f32_e32 v90, 0x7149f2ca, v90
	v_min_f32_e32 v91, 0x7149f2ca, v91
	v_min_f32_e32 v84, 0x7149f2ca, v84
	v_min_f32_e32 v85, 0x7149f2ca, v85
	v_min_f32_e32 v86, 0x7149f2ca, v86
	v_min_f32_e32 v87, 0x7149f2ca, v87
	v_pk_add_f32 v[92:93], v[92:93], s[64:65]
	v_pk_add_f32 v[94:95], v[94:95], s[64:65]
	v_pk_add_f32 v[88:89], v[88:89], s[64:65]
	v_pk_add_f32 v[90:91], v[90:91], s[64:65]
	v_pk_add_f32 v[84:85], v[84:85], s[64:65]
	v_pk_add_f32 v[86:87], v[86:87], s[64:65]
	v_pk_add_f32 v[160:161], v[160:161], s[64:65]
	v_pk_add_f32 v[162:163], v[162:163], s[64:65]
	v_rcp_f32_e32 v152, v92
	v_rcp_f32_e32 v153, v93
	v_rcp_f32_e32 v154, v94
	v_rcp_f32_e32 v155, v95
	v_rcp_f32_e32 v156, v88
	v_rcp_f32_e32 v157, v89
	v_rcp_f32_e32 v158, v90
	v_rcp_f32_e32 v159, v91
	v_rcp_f32_e32 v160, v160
	v_rcp_f32_e32 v161, v161
	v_rcp_f32_e32 v162, v162
	v_rcp_f32_e32 v163, v163
	v_pk_mul_f32 v[152:153], v[88:89], v[152:153]
	v_pk_mul_f32 v[154:155], v[90:91], v[154:155]
	v_pk_mul_f32 v[156:157], v[84:85], v[156:157]
	v_pk_mul_f32 v[158:159], v[86:87], v[158:159]
	v_rcp_f32_e32 v84, v84
	v_rcp_f32_e32 v85, v85
	v_rcp_f32_e32 v86, v86
	v_rcp_f32_e32 v87, v87
	v_pk_mul_f32 v[160:161], v[80:81], v[160:161]
	v_pk_mul_f32 v[162:163], v[82:83], v[162:163]
	v_cvt_pk_bf16_f32 v168, v152, v153
	v_cvt_pk_bf16_f32 v169, v154, v155
	v_cvt_pk_bf16_f32 v172, v156, v157
	v_cvt_pk_bf16_f32 v173, v158, v159
	v_cvt_pk_bf16_f32 v174, v160, v161
	v_cvt_pk_bf16_f32 v175, v162, v163
	v_cvt_pk_bf16_f32 v170, v84, v85
	v_cvt_pk_bf16_f32 v171, v86, v87
	s_nop 1
	v_permlane16_swap_b32_e32 v172, v174
	v_permlane16_swap_b32_e32 v173, v175
	v_permlane16_swap_b32_e32 v168, v170
	v_permlane16_swap_b32_e32 v169, v171
	global_store_dwordx4 v151, v[172:175], s[24:25]
	global_store_dwordx4 v150, v[168:171], s[24:25]
	s_add_u32 s24, s24, 0x8000
	s_addc_u32 s25, s25, 0
	v_pk_mul_f32 v[76:77], v[76:77], s[62:63]
	v_pk_mul_f32 v[78:79], v[78:79], s[62:63]
	v_pk_mul_f32 v[72:73], v[72:73], s[62:63]
	v_pk_mul_f32 v[74:75], v[74:75], s[62:63]
	v_pk_mul_f32 v[68:69], v[68:69], s[62:63]
	v_pk_mul_f32 v[70:71], v[70:71], s[62:63]
	v_pk_mul_f32 v[160:161], v[64:65], s[62:63]
	v_pk_mul_f32 v[162:163], v[66:67], s[62:63]
	v_exp_f32_e32 v76, v76
	v_exp_f32_e32 v77, v77
	v_exp_f32_e32 v78, v78
	v_exp_f32_e32 v79, v79
	v_exp_f32_e32 v72, v72
	v_exp_f32_e32 v73, v73
	v_exp_f32_e32 v74, v74
	v_exp_f32_e32 v75, v75
	v_exp_f32_e32 v68, v68
	v_exp_f32_e32 v69, v69
	v_exp_f32_e32 v70, v70
	v_exp_f32_e32 v71, v71
	v_exp_f32_e32 v160, v160
	v_exp_f32_e32 v161, v161
	v_exp_f32_e32 v162, v162
	v_exp_f32_e32 v163, v163
	v_min_f32_e32 v76, 0x7149f2ca, v76
	v_min_f32_e32 v77, 0x7149f2ca, v77
	v_min_f32_e32 v78, 0x7149f2ca, v78
	v_min_f32_e32 v79, 0x7149f2ca, v79
	v_min_f32_e32 v72, 0x7149f2ca, v72
	v_min_f32_e32 v73, 0x7149f2ca, v73
	v_min_f32_e32 v74, 0x7149f2ca, v74
	v_min_f32_e32 v75, 0x7149f2ca, v75
	v_min_f32_e32 v68, 0x7149f2ca, v68
	v_min_f32_e32 v69, 0x7149f2ca, v69
	v_min_f32_e32 v70, 0x7149f2ca, v70
	v_min_f32_e32 v71, 0x7149f2ca, v71
	v_pk_add_f32 v[76:77], v[76:77], s[64:65]
	v_pk_add_f32 v[78:79], v[78:79], s[64:65]
	v_pk_add_f32 v[72:73], v[72:73], s[64:65]
	v_pk_add_f32 v[74:75], v[74:75], s[64:65]
	v_pk_add_f32 v[68:69], v[68:69], s[64:65]
	v_pk_add_f32 v[70:71], v[70:71], s[64:65]
	v_pk_add_f32 v[160:161], v[160:161], s[64:65]
	v_pk_add_f32 v[162:163], v[162:163], s[64:65]
	v_rcp_f32_e32 v152, v76
	v_rcp_f32_e32 v153, v77
	v_rcp_f32_e32 v154, v78
	v_rcp_f32_e32 v155, v79
	v_rcp_f32_e32 v156, v72
	v_rcp_f32_e32 v157, v73
	v_rcp_f32_e32 v158, v74
	v_rcp_f32_e32 v159, v75
	v_rcp_f32_e32 v160, v160
	v_rcp_f32_e32 v161, v161
	v_rcp_f32_e32 v162, v162
	v_rcp_f32_e32 v163, v163
	v_pk_mul_f32 v[152:153], v[72:73], v[152:153]
	v_pk_mul_f32 v[154:155], v[74:75], v[154:155]
	v_pk_mul_f32 v[156:157], v[68:69], v[156:157]
	v_pk_mul_f32 v[158:159], v[70:71], v[158:159]
;     __device__ __forceinline__ void operator()(f32x4 (&acc)[2][2][4][2], const Unit& u, int wr, int wc, int fr, int fq) const {
;     ...
;         if (mode == 7) {
;             const int row0q = u.pm * BM + wr * 64 + fr; const int ch = 64 * (pn - 32) + 16 * wc + 4 * fq;
; #pragma unroll
;             for (int ai = 0; ai < 2; ++ai)
; #pragma unroll
;                 for (int m = 0; m < 4; ++m) {
;                     bf16_t* rowp = O + (size_t)(row0q + ai * HALF + m * 16) * LDP + ch;
;                     float r0v[4], r1v[4], g2v[4], szv[4];
; #pragma unroll
;                     for (int j = 0; j < 4; ++j) {
;                         const float ea = fminf(__builtin_amdgcn_exp2f(-1.4426950409f * acc[ai][0][m][0][j]), 1e30f);
;                         const float eb = fminf(__builtin_amdgcn_exp2f(-1.4426950409f * acc[ai][0][m][1][j]), 1e30f);
;                         const float ec = fminf(__builtin_amdgcn_exp2f(-1.4426950409f * acc[ai][1][m][0][j]), 1e30f);
;                         const float xz = acc[ai][1][m][1][j];
;                         const float ia = __builtin_amdgcn_rcpf(1.0f + ea), ib = __builtin_amdgcn_rcpf(1.0f + eb), ic = __builtin_amdgcn_rcpf(1.0f + ec);
;                         r0v[j] = (1.0f + eb) * ia; r1v[j] = (1.0f + ec) * ib; g2v[j] = ic; szv[j] = xz * sigmoid_f(xz);
;                     }
;                     u32x2 wr0, wr1, wg2, wsz;
;                     wr0.x = cvt_pk_bf16(r0v[0], r0v[1]); wr0.y = cvt_pk_bf16(r0v[2], r0v[3]);
;                     wr1.x = cvt_pk_bf16(r1v[0], r1v[1]); wr1.y = cvt_pk_bf16(r1v[2], r1v[3]);
;                     wg2.x = cvt_pk_bf16(g2v[0], g2v[1]); wg2.y = cvt_pk_bf16(g2v[2], g2v[3]);
;                     wsz.x = cvt_pk_bf16(szv[0], szv[1]); wsz.y = cvt_pk_bf16(szv[2], szv[3]);
;                     const bool odd = (fq & 1) != 0;
;                     const u32x2 s0 = odd ? wr0 : wg2, s1 = odd ? wr1 : wsz;
;                     u32x2 q0, q1;
;                     q0.x = (unsigned)__shfl_xor((int)s0.x, 16); q0.y = (unsigned)__shfl_xor((int)s0.y, 16);
;                     q1.x = (unsigned)__shfl_xor((int)s1.x, 16); q1.y = (unsigned)__shfl_xor((int)s1.y, 16);
;                     u32x4 o0, o1;
;                     if (!odd) { o0 = (u32x4){wr0.x, wr0.y, q0.x, q0.y}; o1 = (u32x4){wr1.x, wr1.y, q1.x, q1.y}; }
	v_rcp_f32_e32 v68, v68
	v_rcp_f32_e32 v69, v69
	v_rcp_f32_e32 v70, v70
	v_rcp_f32_e32 v71, v71
	v_pk_mul_f32 v[160:161], v[64:65], v[160:161]
	v_pk_mul_f32 v[162:163], v[66:67], v[162:163]
	v_cvt_pk_bf16_f32 v176, v152, v153
	v_cvt_pk_bf16_f32 v177, v154, v155
	v_cvt_pk_bf16_f32 v180, v156, v157
	v_cvt_pk_bf16_f32 v181, v158, v159
	v_cvt_pk_bf16_f32 v182, v160, v161
	v_cvt_pk_bf16_f32 v183, v162, v163
	v_cvt_pk_bf16_f32 v178, v68, v69
	v_cvt_pk_bf16_f32 v179, v70, v71
	s_nop 1
	v_permlane16_swap_b32_e32 v180, v182
	v_permlane16_swap_b32_e32 v181, v183
	v_permlane16_swap_b32_e32 v176, v178
	v_permlane16_swap_b32_e32 v177, v179
	global_store_dwordx4 v151, v[180:183], s[24:25]
	global_store_dwordx4 v150, v[176:179], s[24:25]
	s_add_u32 s24, s24, 0x28000
	s_addc_u32 s25, s25, 0
	v_pk_mul_f32 v[60:61], v[60:61], s[62:63]
	v_pk_mul_f32 v[62:63], v[62:63], s[62:63]
	v_pk_mul_f32 v[56:57], v[56:57], s[62:63]
	v_pk_mul_f32 v[58:59], v[58:59], s[62:63]
	v_pk_mul_f32 v[52:53], v[52:53], s[62:63]
	v_pk_mul_f32 v[54:55], v[54:55], s[62:63]
	v_pk_mul_f32 v[160:161], v[48:49], s[62:63]
	v_pk_mul_f32 v[162:163], v[50:51], s[62:63]
	v_exp_f32_e32 v60, v60
	v_exp_f32_e32 v61, v61
	v_exp_f32_e32 v62, v62
	v_exp_f32_e32 v63, v63
	v_exp_f32_e32 v56, v56
	v_exp_f32_e32 v57, v57
	v_exp_f32_e32 v58, v58
	v_exp_f32_e32 v59, v59
	v_exp_f32_e32 v52, v52
	v_exp_f32_e32 v53, v53
	v_exp_f32_e32 v54, v54
	v_exp_f32_e32 v55, v55
	v_exp_f32_e32 v160, v160
	v_exp_f32_e32 v161, v161
	v_exp_f32_e32 v162, v162
	v_exp_f32_e32 v163, v163
	v_min_f32_e32 v60, 0x7149f2ca, v60
	v_min_f32_e32 v61, 0x7149f2ca, v61
	v_min_f32_e32 v62, 0x7149f2ca, v62
	v_min_f32_e32 v63, 0x7149f2ca, v63
	v_min_f32_e32 v56, 0x7149f2ca, v56
	v_min_f32_e32 v57, 0x7149f2ca, v57
	v_min_f32_e32 v58, 0x7149f2ca, v58
	v_min_f32_e32 v59, 0x7149f2ca, v59
	v_min_f32_e32 v52, 0x7149f2ca, v52
	v_min_f32_e32 v53, 0x7149f2ca, v53
	v_min_f32_e32 v54, 0x7149f2ca, v54
	v_min_f32_e32 v55, 0x7149f2ca, v55
	v_pk_add_f32 v[60:61], v[60:61], s[64:65]
	v_pk_add_f32 v[62:63], v[62:63], s[64:65]
	v_pk_add_f32 v[56:57], v[56:57], s[64:65]
	v_pk_add_f32 v[58:59], v[58:59], s[64:65]
	v_pk_add_f32 v[52:53], v[52:53], s[64:65]
	v_pk_add_f32 v[54:55], v[54:55], s[64:65]
	v_pk_add_f32 v[160:161], v[160:161], s[64:65]
	v_pk_add_f32 v[162:163], v[162:163], s[64:65]
	v_rcp_f32_e32 v152, v60
	v_rcp_f32_e32 v153, v61
	v_rcp_f32_e32 v154, v62
	v_rcp_f32_e32 v155, v63
	v_rcp_f32_e32 v156, v56
	v_rcp_f32_e32 v157, v57
	v_rcp_f32_e32 v158, v58
	v_rcp_f32_e32 v159, v59
	v_rcp_f32_e32 v160, v160
	v_rcp_f32_e32 v161, v161
	v_rcp_f32_e32 v162, v162
	v_rcp_f32_e32 v163, v163
	v_pk_mul_f32 v[152:153], v[56:57], v[152:153]
	v_pk_mul_f32 v[154:155], v[58:59], v[154:155]
	v_pk_mul_f32 v[156:157], v[52:53], v[156:157]
	v_pk_mul_f32 v[158:159], v[54:55], v[158:159]
	v_rcp_f32_e32 v52, v52
	v_rcp_f32_e32 v53, v53
	v_rcp_f32_e32 v54, v54
	v_rcp_f32_e32 v55, v55
	v_pk_mul_f32 v[160:161], v[48:49], v[160:161]
	v_pk_mul_f32 v[162:163], v[50:51], v[162:163]
	v_cvt_pk_bf16_f32 v168, v152, v153
	v_cvt_pk_bf16_f32 v169, v154, v155
	v_cvt_pk_bf16_f32 v172, v156, v157
	v_cvt_pk_bf16_f32 v173, v158, v159
	v_cvt_pk_bf16_f32 v174, v160, v161
	v_cvt_pk_bf16_f32 v175, v162, v163
	v_cvt_pk_bf16_f32 v170, v52, v53
	v_cvt_pk_bf16_f32 v171, v54, v55
	s_nop 1
	v_permlane16_swap_b32_e32 v172, v174
	v_permlane16_swap_b32_e32 v173, v175
	v_permlane16_swap_b32_e32 v168, v170
	v_permlane16_swap_b32_e32 v169, v171
	global_store_dwordx4 v151, v[172:175], s[24:25]
	global_store_dwordx4 v150, v[168:171], s[24:25]
	s_add_u32 s24, s24, 0x8000
	s_addc_u32 s25, s25, 0
	v_pk_mul_f32 v[44:45], v[44:45], s[62:63]
	v_pk_mul_f32 v[46:47], v[46:47], s[62:63]
	v_pk_mul_f32 v[40:41], v[40:41], s[62:63]
	v_pk_mul_f32 v[42:43], v[42:43], s[62:63]
	v_pk_mul_f32 v[36:37], v[36:37], s[62:63]
	v_pk_mul_f32 v[38:39], v[38:39], s[62:63]
	v_pk_mul_f32 v[160:161], v[32:33], s[62:63]
	v_pk_mul_f32 v[162:163], v[34:35], s[62:63]
	v_exp_f32_e32 v44, v44
	v_exp_f32_e32 v45, v45
	v_exp_f32_e32 v46, v46
	v_exp_f32_e32 v47, v47
	v_exp_f32_e32 v40, v40
	v_exp_f32_e32 v41, v41
	v_exp_f32_e32 v42, v42
	v_exp_f32_e32 v43, v43
	v_exp_f32_e32 v36, v36
	v_exp_f32_e32 v37, v37
	v_exp_f32_e32 v38, v38
	v_exp_f32_e32 v39, v39
	v_exp_f32_e32 v160, v160
	v_exp_f32_e32 v161, v161
	v_exp_f32_e32 v162, v162
	v_exp_f32_e32 v163, v163
	v_min_f32_e32 v44, 0x7149f2ca, v44
	v_min_f32_e32 v45, 0x7149f2ca, v45
	v_min_f32_e32 v46, 0x7149f2ca, v46
	v_min_f32_e32 v47, 0x7149f2ca, v47
	v_min_f32_e32 v40, 0x7149f2ca, v40
	v_min_f32_e32 v41, 0x7149f2ca, v41
	v_min_f32_e32 v42, 0x7149f2ca, v42
	v_min_f32_e32 v43, 0x7149f2ca, v43
	v_min_f32_e32 v36, 0x7149f2ca, v36
	v_min_f32_e32 v37, 0x7149f2ca, v37
	v_min_f32_e32 v38, 0x7149f2ca, v38
	v_min_f32_e32 v39, 0x7149f2ca, v39
	v_pk_add_f32 v[44:45], v[44:45], s[64:65]
	v_pk_add_f32 v[46:47], v[46:47], s[64:65]
	v_pk_add_f32 v[40:41], v[40:41], s[64:65]
	v_pk_add_f32 v[42:43], v[42:43], s[64:65]
	v_pk_add_f32 v[36:37], v[36:37], s[64:65]
	v_pk_add_f32 v[38:39], v[38:39], s[64:65]
	v_pk_add_f32 v[160:161], v[160:161], s[64:65]
	v_pk_add_f32 v[162:163], v[162:163], s[64:65]
	v_rcp_f32_e32 v152, v44
	v_rcp_f32_e32 v153, v45
	v_rcp_f32_e32 v154, v46
	v_rcp_f32_e32 v155, v47
	v_rcp_f32_e32 v156, v40
	v_rcp_f32_e32 v157, v41
	v_rcp_f32_e32 v158, v42
	v_rcp_f32_e32 v159, v43
	v_rcp_f32_e32 v160, v160
	v_rcp_f32_e32 v161, v161
	v_rcp_f32_e32 v162, v162
	v_rcp_f32_e32 v163, v163
	v_pk_mul_f32 v[152:153], v[40:41], v[152:153]
	v_pk_mul_f32 v[154:155], v[42:43], v[154:155]
	v_pk_mul_f32 v[156:157], v[36:37], v[156:157]
	v_pk_mul_f32 v[158:159], v[38:39], v[158:159]
	v_rcp_f32_e32 v36, v36
	v_rcp_f32_e32 v37, v37
;     __device__ __forceinline__ void operator()(f32x4 (&acc)[2][2][4][2], const Unit& u, int wr, int wc, int fr, int fq) const {
;     ...
;         if (mode == 7) {
;             const int row0q = u.pm * BM + wr * 64 + fr; const int ch = 64 * (pn - 32) + 16 * wc + 4 * fq;
; #pragma unroll
;             for (int ai = 0; ai < 2; ++ai)
; #pragma unroll
;                 for (int m = 0; m < 4; ++m) {
;                     bf16_t* rowp = O + (size_t)(row0q + ai * HALF + m * 16) * LDP + ch;
;                     float r0v[4], r1v[4], g2v[4], szv[4];
; #pragma unroll
;                     for (int j = 0; j < 4; ++j) {
;                         const float ea = fminf(__builtin_amdgcn_exp2f(-1.4426950409f * acc[ai][0][m][0][j]), 1e30f);
;                         const float eb = fminf(__builtin_amdgcn_exp2f(-1.4426950409f * acc[ai][0][m][1][j]), 1e30f);
;                         const float ec = fminf(__builtin_amdgcn_exp2f(-1.4426950409f * acc[ai][1][m][0][j]), 1e30f);
;                         const float xz = acc[ai][1][m][1][j];
;                         const float ia = __builtin_amdgcn_rcpf(1.0f + ea), ib = __builtin_amdgcn_rcpf(1.0f + eb), ic = __builtin_amdgcn_rcpf(1.0f + ec);
;                         r0v[j] = (1.0f + eb) * ia; r1v[j] = (1.0f + ec) * ib; g2v[j] = ic; szv[j] = xz * sigmoid_f(xz);
;                     }
;                     u32x2 wr0, wr1, wg2, wsz;
;                     wr0.x = cvt_pk_bf16(r0v[0], r0v[1]); wr0.y = cvt_pk_bf16(r0v[2], r0v[3]);
;                     wr1.x = cvt_pk_bf16(r1v[0], r1v[1]); wr1.y = cvt_pk_bf16(r1v[2], r1v[3]);
;                     wg2.x = cvt_pk_bf16(g2v[0], g2v[1]); wg2.y = cvt_pk_bf16(g2v[2], g2v[3]);
;                     wsz.x = cvt_pk_bf16(szv[0], szv[1]); wsz.y = cvt_pk_bf16(szv[2], szv[3]);
;                     const bool odd = (fq & 1) != 0;
;                     const u32x2 s0 = odd ? wr0 : wg2, s1 = odd ? wr1 : wsz;
;                     u32x2 q0, q1;
;                     q0.x = (unsigned)__shfl_xor((int)s0.x, 16); q0.y = (unsigned)__shfl_xor((int)s0.y, 16);
;                     q1.x = (unsigned)__shfl_xor((int)s1.x, 16); q1.y = (unsigned)__shfl_xor((int)s1.y, 16);
;                     u32x4 o0, o1;
;                     if (!odd) { o0 = (u32x4){wr0.x, wr0.y, q0.x, q0.y}; o1 = (u32x4){wr1.x, wr1.y, q1.x, q1.y}; }
	v_rcp_f32_e32 v38, v38
	v_rcp_f32_e32 v39, v39
	v_pk_mul_f32 v[160:161], v[32:33], v[160:161]
	v_pk_mul_f32 v[162:163], v[34:35], v[162:163]
	v_cvt_pk_bf16_f32 v176, v152, v153
	v_cvt_pk_bf16_f32 v177, v154, v155
	v_cvt_pk_bf16_f32 v180, v156, v157
	v_cvt_pk_bf16_f32 v181, v158, v159
	v_cvt_pk_bf16_f32 v182, v160, v161
	v_cvt_pk_bf16_f32 v183, v162, v163
	v_cvt_pk_bf16_f32 v178, v36, v37
	v_cvt_pk_bf16_f32 v179, v38, v39
	s_nop 1
	v_permlane16_swap_b32_e32 v180, v182
	v_permlane16_swap_b32_e32 v181, v183
	v_permlane16_swap_b32_e32 v176, v178
	v_permlane16_swap_b32_e32 v177, v179
	global_store_dwordx4 v151, v[180:183], s[24:25]
	global_store_dwordx4 v150, v[176:179], s[24:25]
	s_add_u32 s24, s24, 0x8000
	s_addc_u32 s25, s25, 0
	v_pk_mul_f32 v[28:29], v[28:29], s[62:63]
	v_pk_mul_f32 v[30:31], v[30:31], s[62:63]
	v_pk_mul_f32 v[24:25], v[24:25], s[62:63]
	v_pk_mul_f32 v[26:27], v[26:27], s[62:63]
	v_pk_mul_f32 v[20:21], v[20:21], s[62:63]
	v_pk_mul_f32 v[22:23], v[22:23], s[62:63]
	v_pk_mul_f32 v[160:161], v[16:17], s[62:63]
	v_pk_mul_f32 v[162:163], v[18:19], s[62:63]
	v_exp_f32_e32 v28, v28
	v_exp_f32_e32 v29, v29
	v_exp_f32_e32 v30, v30
	v_exp_f32_e32 v31, v31
	v_exp_f32_e32 v24, v24
	v_exp_f32_e32 v25, v25
	v_exp_f32_e32 v26, v26
	v_exp_f32_e32 v27, v27
	v_exp_f32_e32 v20, v20
	v_exp_f32_e32 v21, v21
	v_exp_f32_e32 v22, v22
	v_exp_f32_e32 v23, v23
	v_exp_f32_e32 v160, v160
	v_exp_f32_e32 v161, v161
	v_exp_f32_e32 v162, v162
	v_exp_f32_e32 v163, v163
	v_min_f32_e32 v28, 0x7149f2ca, v28
	v_min_f32_e32 v29, 0x7149f2ca, v29
	v_min_f32_e32 v30, 0x7149f2ca, v30
	v_min_f32_e32 v31, 0x7149f2ca, v31
	v_min_f32_e32 v24, 0x7149f2ca, v24
	v_min_f32_e32 v25, 0x7149f2ca, v25
	v_min_f32_e32 v26, 0x7149f2ca, v26
	v_min_f32_e32 v27, 0x7149f2ca, v27
	v_min_f32_e32 v20, 0x7149f2ca, v20
	v_min_f32_e32 v21, 0x7149f2ca, v21
	v_min_f32_e32 v22, 0x7149f2ca, v22
	v_min_f32_e32 v23, 0x7149f2ca, v23
	v_pk_add_f32 v[28:29], v[28:29], s[64:65]
	v_pk_add_f32 v[30:31], v[30:31], s[64:65]
	v_pk_add_f32 v[24:25], v[24:25], s[64:65]
	v_pk_add_f32 v[26:27], v[26:27], s[64:65]
	v_pk_add_f32 v[20:21], v[20:21], s[64:65]
	v_pk_add_f32 v[22:23], v[22:23], s[64:65]
	v_pk_add_f32 v[160:161], v[160:161], s[64:65]
	v_pk_add_f32 v[162:163], v[162:163], s[64:65]
	v_rcp_f32_e32 v152, v28
	v_rcp_f32_e32 v153, v29
	v_rcp_f32_e32 v154, v30
	v_rcp_f32_e32 v155, v31
	v_rcp_f32_e32 v156, v24
	v_rcp_f32_e32 v157, v25
	v_rcp_f32_e32 v158, v26
	v_rcp_f32_e32 v159, v27
	v_rcp_f32_e32 v160, v160
	v_rcp_f32_e32 v161, v161
	v_rcp_f32_e32 v162, v162
	v_rcp_f32_e32 v163, v163
	v_pk_mul_f32 v[152:153], v[24:25], v[152:153]
	v_pk_mul_f32 v[154:155], v[26:27], v[154:155]
	v_pk_mul_f32 v[156:157], v[20:21], v[156:157]
	v_pk_mul_f32 v[158:159], v[22:23], v[158:159]
	v_rcp_f32_e32 v20, v20
	v_rcp_f32_e32 v21, v21
	v_rcp_f32_e32 v22, v22
	v_rcp_f32_e32 v23, v23
	v_pk_mul_f32 v[160:161], v[16:17], v[160:161]
	v_pk_mul_f32 v[162:163], v[18:19], v[162:163]
	v_cvt_pk_bf16_f32 v168, v152, v153
	v_cvt_pk_bf16_f32 v169, v154, v155
	v_cvt_pk_bf16_f32 v172, v156, v157
	v_cvt_pk_bf16_f32 v173, v158, v159
	v_cvt_pk_bf16_f32 v174, v160, v161
	v_cvt_pk_bf16_f32 v175, v162, v163
	v_cvt_pk_bf16_f32 v170, v20, v21
	v_cvt_pk_bf16_f32 v171, v22, v23
	s_nop 1
	v_permlane16_swap_b32_e32 v172, v174
	v_permlane16_swap_b32_e32 v173, v175
	v_permlane16_swap_b32_e32 v168, v170
	v_permlane16_swap_b32_e32 v169, v171
	global_store_dwordx4 v151, v[172:175], s[24:25]
	global_store_dwordx4 v150, v[168:171], s[24:25]
	s_add_u32 s24, s24, 0x8000
	s_addc_u32 s25, s25, 0
	v_pk_mul_f32 v[12:13], v[12:13], s[62:63]
	v_pk_mul_f32 v[14:15], v[14:15], s[62:63]
	v_pk_mul_f32 v[8:9], v[8:9], s[62:63]
	v_pk_mul_f32 v[10:11], v[10:11], s[62:63]
	v_pk_mul_f32 v[4:5], v[4:5], s[62:63]
	v_pk_mul_f32 v[6:7], v[6:7], s[62:63]
	v_pk_mul_f32 v[160:161], v[0:1], s[62:63]
	v_pk_mul_f32 v[162:163], v[2:3], s[62:63]
	v_exp_f32_e32 v12, v12
	v_exp_f32_e32 v13, v13
	v_exp_f32_e32 v14, v14
	v_exp_f32_e32 v15, v15
	v_exp_f32_e32 v8, v8
	v_exp_f32_e32 v9, v9
	v_exp_f32_e32 v10, v10
	v_exp_f32_e32 v11, v11
	v_exp_f32_e32 v4, v4
	v_exp_f32_e32 v5, v5
	v_exp_f32_e32 v6, v6
	v_exp_f32_e32 v7, v7
	v_exp_f32_e32 v160, v160
	v_exp_f32_e32 v161, v161
	v_exp_f32_e32 v162, v162
	v_exp_f32_e32 v163, v163
	v_min_f32_e32 v12, 0x7149f2ca, v12
	v_min_f32_e32 v13, 0x7149f2ca, v13
	v_min_f32_e32 v14, 0x7149f2ca, v14
	v_min_f32_e32 v15, 0x7149f2ca, v15
	v_min_f32_e32 v8, 0x7149f2ca, v8
	v_min_f32_e32 v9, 0x7149f2ca, v9
	v_min_f32_e32 v10, 0x7149f2ca, v10
	v_min_f32_e32 v11, 0x7149f2ca, v11
	v_min_f32_e32 v4, 0x7149f2ca, v4
	v_min_f32_e32 v5, 0x7149f2ca, v5
	v_min_f32_e32 v6, 0x7149f2ca, v6
	v_min_f32_e32 v7, 0x7149f2ca, v7
	v_pk_add_f32 v[12:13], v[12:13], s[64:65]
	v_pk_add_f32 v[14:15], v[14:15], s[64:65]
	v_pk_add_f32 v[8:9], v[8:9], s[64:65]
	v_pk_add_f32 v[10:11], v[10:11], s[64:65]
	v_pk_add_f32 v[4:5], v[4:5], s[64:65]
	v_pk_add_f32 v[6:7], v[6:7], s[64:65]
	v_pk_add_f32 v[160:161], v[160:161], s[64:65]
	v_pk_add_f32 v[162:163], v[162:163], s[64:65]
	v_rcp_f32_e32 v152, v12
	v_rcp_f32_e32 v153, v13
	v_rcp_f32_e32 v154, v14
	v_rcp_f32_e32 v155, v15
	v_rcp_f32_e32 v156, v8
	v_rcp_f32_e32 v157, v9
	v_rcp_f32_e32 v158, v10
	v_rcp_f32_e32 v159, v11
	v_rcp_f32_e32 v160, v160
	v_rcp_f32_e32 v161, v161
	v_rcp_f32_e32 v162, v162
	v_rcp_f32_e32 v163, v163
	v_pk_mul_f32 v[152:153], v[8:9], v[152:153]
	v_pk_mul_f32 v[154:155], v[10:11], v[154:155]
	v_pk_mul_f32 v[156:157], v[4:5], v[156:157]
	v_pk_mul_f32 v[158:159], v[6:7], v[158:159]
	v_rcp_f32_e32 v4, v4
	v_rcp_f32_e32 v5, v5
	v_rcp_f32_e32 v6, v6
	v_rcp_f32_e32 v7, v7
	v_pk_mul_f32 v[160:161], v[0:1], v[160:161]
	v_pk_mul_f32 v[162:163], v[2:3], v[162:163]
	v_cvt_pk_bf16_f32 v176, v152, v153
	v_cvt_pk_bf16_f32 v177, v154, v155
	v_cvt_pk_bf16_f32 v180, v156, v157
	v_cvt_pk_bf16_f32 v181, v158, v159
	v_cvt_pk_bf16_f32 v182, v160, v161
	v_cvt_pk_bf16_f32 v183, v162, v163
	v_cvt_pk_bf16_f32 v178, v4, v5
	v_cvt_pk_bf16_f32 v179, v6, v7
	s_nop 1
	v_permlane16_swap_b32_e32 v180, v182
	v_permlane16_swap_b32_e32 v181, v183
	v_permlane16_swap_b32_e32 v176, v178
	v_permlane16_swap_b32_e32 v177, v179
	global_store_dwordx4 v151, v[180:183], s[24:25]
	global_store_dwordx4 v150, v[176:179], s[24:25]
	s_branch .LBB0_298
